# combo8 + RoPE epilogue table fetches paired (two round trips per 16-column group instead of four)
# baseline (speedup 1.0000x reference)
;     __device__ __forceinline__ void operator()(const f32x4 (&acc)[2][2][4][2], const Unit& u, int wr, int wc, int fr, int fq) const {
;         const int row0 = u.pm * BM + wr * 64 + fr;
;         if (u.pn < 2) {
;             const int head = 4 * u.pn + wc; const bool isq = head < 6;
;             const float* g = isq ? gq : gk; const float gs = isq ? C2 : 1.0f;
;             f32x4 gv[2][2];
; #pragma unroll
;             for (int bj = 0; bj < 2; ++bj)
; #pragma unroll
;                 for (int n = 0; n < 2; ++n) gv[bj][n] = *(const f32x4*)(g + 32 * bj + 8 * fq + 4 * n) * gs;
;             const int ocol = 64 * head + 8 * fq;
; #pragma unroll
;             for (int ai = 0; ai < 2; ++ai)
; #pragma unroll
;                 for (int m = 0; m < 4; ++m) {
;                     const int row = row0 + ai * HALF + m * 16;
;                     const int w = row >= RPB ? row - RPB : row;
;                     f32x4 x[2][2]; float ss = 0.f;
; #pragma unroll
;                     for (int bj = 0; bj < 2; ++bj)
; #pragma unroll
;                         for (int n = 0; n < 2; ++n) { x[bj][n] = acc[ai][bj][m][n]; const f32x4 q = x[bj][n] * x[bj][n]; ss += (q[0] + q[1]) + (q[2] + q[3]); }
;                     ss += __shfl_xor(ss, 16); ss += __shfl_xor(ss, 32);
;                     const float rinv = 1.0f / sqrtf(ss * (1.0f / 64.0f) + LN_EPS);
; #pragma unroll
;                     for (int bj = 0; bj < 2; ++bj)
; #pragma unroll
;                         for (int n = 0; n < 2; ++n) x[bj][n] = x[bj][n] * rinv * gv[bj][n];
;                     if (w < SEQ) {
.LBB0_257:
	s_and_b64 vcc, exec, s[0:1]
	s_cbranch_vccz .LBB0_341
	s_lshl_b32 s0, s24, 2
	s_or_b32 s2, s0, s40
	s_cmp_lt_i32 s2, 6
	s_cselect_b64 vcc, -1, 0
	v_readlane_b32 s44, v253, 25
	s_and_b64 s[0:1], vcc, exec
	v_readlane_b32 s50, v253, 31
	v_readlane_b32 s51, v253, 32
	v_readlane_b32 s52, v253, 33
	v_readlane_b32 s53, v253, 34
	s_cselect_b32 s3, s51, s53
	s_cselect_b32 s8, s50, s52
	s_lshl_b64 s[0:1], s[60:61], 2
	s_add_u32 s0, s8, s0
	s_addc_u32 s1, s3, s1
	global_load_dwordx4 v[134:137], v172, s[0:1]
	global_load_dwordx4 v[138:141], v172, s[0:1] offset:16
	global_load_dwordx4 v[166:169], v172, s[0:1] offset:128
	global_load_dwordx4 v[176:179], v172, s[0:1] offset:144
	v_and_b32_e32 v186, 64, v220
	v_pk_mul_f32 v[158:159], v[132:133], v[132:133]
	v_pk_mul_f32 v[160:161], v[130:131], v[130:131]
	v_pk_mul_f32 v[162:163], v[128:129], v[128:129]
	v_pk_mul_f32 v[164:165], v[126:127], v[126:127]
	v_add_u32_e32 v189, 64, v186
	v_pk_mov_b32 v[186:187], v[160:161], v[158:159] op_sel:[1,0]
	v_mov_b32_e32 v161, v159
	v_pk_mov_b32 v[158:159], v[164:165], v[162:163] op_sel:[1,0]
	v_mov_b32_e32 v165, v163
	v_pk_add_f32 v[160:161], v[186:187], v[160:161]
	v_pk_add_f32 v[158:159], v[158:159], v[164:165]
	v_pk_mul_f32 v[174:175], v[124:125], v[124:125]
	v_pk_mul_f32 v[180:181], v[122:123], v[122:123]
	v_pk_mul_f32 v[182:183], v[120:121], v[120:121]
	v_pk_mul_f32 v[184:185], v[118:119], v[118:119]
	v_pk_add_f32 v[160:161], v[160:161], v[160:161] op_sel_hi:[0,1]
	v_pk_add_f32 v[158:159], v[158:159], v[158:159] op_sel_hi:[0,1]
	v_xor_b32_e32 v188, 16, v220
	v_add_f32_e32 v163, v180, v181
	v_add_f32_e32 v175, v174, v175
	v_mov_b32_e32 v162, v184
	v_mov_b32_e32 v174, v185
	v_mov_b32_e32 v158, v182
	v_mov_b32_e32 v160, v183
	v_cndmask_b32_e32 v0, 1.0, v219, vcc
	v_cmp_lt_i32_e32 vcc, v188, v189
	v_pk_add_f32 v[162:163], v[162:163], v[174:175]
	v_pk_add_f32 v[158:159], v[158:159], v[160:161]
	v_cndmask_b32_e32 v180, v220, v188, vcc
	v_pk_add_f32 v[158:159], v[162:163], v[158:159]
	v_lshlrev_b32_e32 v175, 2, v180
	v_add_f32_e32 v158, v158, v159
	ds_bpermute_b32 v159, v175, v158
	v_xor_b32_e32 v160, 32, v220
	v_cmp_lt_i32_e32 vcc, v160, v189
	v_add_u32_e32 v183, 0xffffdf00, v173
	v_readlane_b32 s45, v253, 26
	v_cndmask_b32_e32 v160, v220, v160, vcc
	v_lshlrev_b32_e32 v174, 2, v160
	s_waitcnt lgkmcnt(0)
	v_add_f32_e32 v158, v158, v159
	ds_bpermute_b32 v159, v174, v158
	v_readlane_b32 s46, v253, 27
	v_readlane_b32 s47, v253, 28
	v_readlane_b32 s48, v253, 29
	v_readlane_b32 s49, v253, 30
	s_waitcnt lgkmcnt(0)
	v_add_f32_e32 v158, v158, v159
	v_fmamk_f32 v158, v158, 0x3c800000, v216
	v_mul_f32_e32 v159, 0x4f800000, v158
	v_cmp_gt_f32_e32 vcc, s69, v158
	v_readlane_b32 s54, v253, 35
	v_readlane_b32 s55, v253, 36
	v_cndmask_b32_e32 v158, v158, v159, vcc
	v_sqrt_f32_e32 v159, v158
	v_readlane_b32 s56, v253, 37
	v_readlane_b32 s57, v253, 38
	v_readlane_b32 s58, v253, 39
	v_add_u32_e32 v160, -1, v159
	v_add_u32_e32 v161, 1, v159
	v_fma_f32 v162, -v160, v159, v158
	v_fma_f32 v163, -v161, v159, v158
	v_cmp_ge_f32_e64 s[0:1], 0, v162
	v_readlane_b32 s59, v253, 40
	s_waitcnt vmcnt(0)
	v_pk_mul_f32 v[164:165], v[0:1], v[134:135] op_sel_hi:[0,1]
	v_cndmask_b32_e64 v159, v159, v160, s[0:1]
	v_cmp_lt_f32_e64 s[0:1], 0, v163
	v_pk_mul_f32 v[162:163], v[0:1], v[136:137] op_sel_hi:[0,1]
	v_pk_mul_f32 v[134:135], v[0:1], v[178:179] op_sel_hi:[0,1]
	v_cndmask_b32_e64 v159, v159, v161, s[0:1]
	v_mul_f32_e32 v160, 0x37800000, v159
	v_cndmask_b32_e32 v159, v159, v160, vcc
	v_cmp_class_f32_e32 vcc, v158, v217
	v_pk_mul_f32 v[160:161], v[0:1], v[138:139] op_sel_hi:[0,1]
	v_pk_mul_f32 v[138:139], v[0:1], v[168:169] op_sel_hi:[0,1]
	v_cndmask_b32_e32 v180, v159, v158, vcc
	v_div_scale_f32 v181, s[0:1], v180, v180, 1.0
	v_rcp_f32_e32 v182, v181
	v_div_scale_f32 v184, vcc, 1.0, v180, 1.0
	v_pk_mul_f32 v[136:137], v[0:1], v[176:177] op_sel_hi:[0,1]
	v_fma_f32 v158, -v181, v182, 1.0
	v_fmac_f32_e32 v182, v158, v182
	v_mul_f32_e32 v185, v184, v182
	v_pk_mul_f32 v[158:159], v[0:1], v[140:141] op_sel_hi:[0,1]
	v_pk_mul_f32 v[140:141], v[0:1], v[166:167] op_sel_hi:[0,1]
	v_fma_f32 v0, -v181, v185, v184
	v_fmac_f32_e32 v185, v0, v182
	v_fma_f32 v0, -v181, v185, v184
	v_div_fmas_f32 v0, v0, v182, v185
	v_div_fixup_f32 v0, v0, v180, 1.0
	v_pk_mul_f32 v[166:167], v[130:131], v[0:1] op_sel_hi:[1,0]
	v_pk_mul_f32 v[130:131], v[132:133], v[0:1] op_sel_hi:[1,0]
	v_pk_mul_f32 v[132:133], v[164:165], v[166:167]
	v_pk_mul_f32 v[166:167], v[126:127], v[0:1] op_sel_hi:[1,0]
	v_cmp_lt_i32_e32 vcc, s67, v173
	v_pk_mul_f32 v[126:127], v[128:129], v[0:1] op_sel_hi:[1,0]
	v_pk_mul_f32 v[128:129], v[160:161], v[166:167]
	v_pk_mul_f32 v[166:167], v[122:123], v[0:1] op_sel_hi:[1,0]
	v_pk_mul_f32 v[122:123], v[124:125], v[0:1] op_sel_hi:[1,0]
	v_pk_mul_f32 v[118:119], v[118:119], v[0:1] op_sel_hi:[1,0]
	v_pk_mul_f32 v[120:121], v[120:121], v[0:1] op_sel_hi:[1,0]
	v_cndmask_b32_e32 v0, v173, v183, vcc
	v_pk_mul_f32 v[130:131], v[162:163], v[130:131]
	v_pk_mul_f32 v[126:127], v[158:159], v[126:127]
	v_pk_mul_f32 v[122:123], v[138:139], v[122:123]
	v_pk_mul_f32 v[168:169], v[140:141], v[166:167]
	v_pk_mul_f32 v[124:125], v[134:135], v[120:121]
	v_pk_mul_f32 v[166:167], v[136:137], v[118:119]
	v_cmp_gt_i32_e32 vcc, s66, v0
	s_and_saveexec_b64 s[0:1], vcc
	s_cbranch_execz .LBB0_260
; __device__ __forceinline__ unsigned cvt_pk_bf16(float lo, float hi) { unsigned r; asm volatile("v_cvt_pk_bf16_f32 %0, %1, %2" : "=v"(r) : "v"(lo), "v"(hi)); return r; }
;     __device__ __forceinline__ void operator()(const f32x4 (&acc)[2][2][4][2], const Unit& u, int wr, int wc, int fr, int fq) const {
;     ...
;                     if (w < SEQ) {
; #pragma unroll
;                         for (int bj = 0; bj < 2; ++bj) {
;                             const int pos = bj ? (w & 63) : (w >> 6);
; #pragma unroll
;                             for (int n = 0; n < 2; ++n) {
;                                 const f32x4 cs = *(const f32x4*)(tcos + pos * 16 + 8 * (fq & 1) + 4 * n);
;                                 const f32x4 sn = *(const f32x4*)(tsin + pos * 16 + 8 * (fq & 1) + 4 * n);
;                                 f32x4 p; p[0] = __shfl_xor(x[bj][n][0], 32); p[1] = __shfl_xor(x[bj][n][1], 32); p[2] = __shfl_xor(x[bj][n][2], 32); p[3] = __shfl_xor(x[bj][n][3], 32);
;                                 const f32x4 sgn = (fq < 2) ? -sn : sn;
;                                 x[bj][n] = x[bj][n] * cs + p * sgn;
;                             }
;                         }
;                     }
;                     bf16_t* rowp = O + (size_t)row * DIN + ocol;
; #pragma unroll
;                     for (int bj = 0; bj < 2; ++bj) { u32x4 wv; wv.x = cvt_pk_bf16(x[bj][0][0], x[bj][0][1]); wv.y = cvt_pk_bf16(x[bj][0][2], x[bj][0][3]); wv.z = cvt_pk_bf16(x[bj][1][0], x[bj][1][1]); wv.w = cvt_pk_bf16(x[bj][1][2], x[bj][1][3]);
;                         *(u32x4*)(rowp + 32 * bj) = wv; }
	v_ashrrev_i32_e32 v118, 2, v0
	v_and_b32_e32 v118, -16, v118
	v_ashrrev_i32_e32 v119, 31, v118
	v_lshlrev_b64 v[118:119], 2, v[118:119]
	v_lshl_add_u64 v[180:181], v[150:151], 0, v[118:119]
	v_lshl_add_u64 v[182:183], v[152:153], 0, v[118:119]
	flat_load_dwordx4 v[118:121], v[180:181]
	flat_load_dwordx4 v[176:179], v[182:183]
	flat_load_dwordx4 v[240:243], v[180:181] offset:16
	flat_load_dwordx4 v[244:247], v[182:183] offset:16
	ds_bpermute_b32 v184, v174, v132
	ds_bpermute_b32 v185, v174, v133
	ds_bpermute_b32 v186, v174, v130
	ds_bpermute_b32 v187, v174, v131
	v_lshlrev_b32_e32 v0, 6, v0
	v_and_b32_e32 v0, 0x3c0, v0
	s_waitcnt vmcnt(0) lgkmcnt(0)
	v_xor_b32_e32 v188, 0x80000000, v176
	v_xor_b32_e32 v189, 0x80000000, v177
	v_xor_b32_e32 v190, 0x80000000, v178
	v_xor_b32_e32 v191, 0x80000000, v179
	v_cndmask_b32_e64 v179, v179, v191, s[4:5]
	v_cndmask_b32_e64 v178, v178, v190, s[4:5]
	v_cndmask_b32_e64 v177, v177, v189, s[4:5]
	v_cndmask_b32_e64 v176, v176, v188, s[4:5]
	v_pk_mul_f32 v[176:177], v[176:177], v[184:185]
	v_pk_mul_f32 v[178:179], v[178:179], v[186:187]
	v_pk_fma_f32 v[132:133], v[132:133], v[118:119], v[176:177]
	v_pk_fma_f32 v[130:131], v[130:131], v[120:121], v[178:179]
	ds_bpermute_b32 v180, v174, v128
	ds_bpermute_b32 v181, v174, v129
	ds_bpermute_b32 v182, v174, v126
	ds_bpermute_b32 v183, v174, v127
	s_waitcnt vmcnt(0) lgkmcnt(0)
	v_xor_b32_e32 v184, 0x80000000, v244
	v_xor_b32_e32 v185, 0x80000000, v245
	v_xor_b32_e32 v186, 0x80000000, v246
	v_xor_b32_e32 v187, 0x80000000, v247
	v_cndmask_b32_e64 v247, v247, v187, s[4:5]
	v_cndmask_b32_e64 v246, v246, v186, s[4:5]
	v_cndmask_b32_e64 v245, v245, v185, s[4:5]
	v_cndmask_b32_e64 v244, v244, v184, s[4:5]
	v_pk_mul_f32 v[244:245], v[244:245], v[180:181]
	v_pk_mul_f32 v[246:247], v[246:247], v[182:183]
	v_lshl_add_u64 v[180:181], v[150:151], 0, v[0:1]
	v_pk_fma_f32 v[126:127], v[126:127], v[242:243], v[246:247]
	v_pk_fma_f32 v[128:129], v[128:129], v[240:241], v[244:245]
	v_lshl_add_u64 v[182:183], v[152:153], 0, v[0:1]
	flat_load_dwordx4 v[118:121], v[180:181]
	flat_load_dwordx4 v[176:179], v[182:183]
	flat_load_dwordx4 v[240:243], v[180:181] offset:16
	flat_load_dwordx4 v[244:247], v[182:183] offset:16
	ds_bpermute_b32 v184, v174, v168
	ds_bpermute_b32 v185, v174, v169
	ds_bpermute_b32 v186, v174, v122
	ds_bpermute_b32 v187, v174, v123
	s_waitcnt vmcnt(0) lgkmcnt(0)
	v_xor_b32_e32 v0, 0x80000000, v176
	v_xor_b32_e32 v188, 0x80000000, v177
	v_xor_b32_e32 v189, 0x80000000, v178
	v_xor_b32_e32 v190, 0x80000000, v179
	v_cndmask_b32_e64 v179, v179, v190, s[4:5]
	v_cndmask_b32_e64 v178, v178, v189, s[4:5]
	v_cndmask_b32_e64 v177, v177, v188, s[4:5]
	v_cndmask_b32_e64 v176, v176, v0, s[4:5]
	v_pk_mul_f32 v[176:177], v[176:177], v[184:185]
	v_pk_mul_f32 v[178:179], v[178:179], v[186:187]
	v_pk_fma_f32 v[168:169], v[168:169], v[118:119], v[176:177]
	v_pk_fma_f32 v[122:123], v[122:123], v[120:121], v[178:179]
	ds_bpermute_b32 v180, v174, v166
	ds_bpermute_b32 v181, v174, v167
	ds_bpermute_b32 v182, v174, v124
	ds_bpermute_b32 v183, v174, v125
	s_waitcnt vmcnt(0) lgkmcnt(0)
	v_xor_b32_e32 v0, 0x80000000, v244
	v_xor_b32_e32 v184, 0x80000000, v245
	v_xor_b32_e32 v185, 0x80000000, v246
	v_xor_b32_e32 v186, 0x80000000, v247
	v_cndmask_b32_e64 v247, v247, v186, s[4:5]
	v_cndmask_b32_e64 v246, v246, v185, s[4:5]
	v_cndmask_b32_e64 v245, v245, v184, s[4:5]
	v_cndmask_b32_e64 v244, v244, v0, s[4:5]
	v_pk_mul_f32 v[244:245], v[244:245], v[180:181]
	v_pk_mul_f32 v[246:247], v[246:247], v[182:183]
	v_pk_fma_f32 v[166:167], v[166:167], v[240:241], v[244:245]
	v_pk_fma_f32 v[124:125], v[124:125], v[242:243], v[246:247]
.LBB0_260:
	s_or_b64 exec, exec, s[0:1]
	v_pk_mul_f32 v[176:177], v[116:117], v[116:117]
	v_pk_mul_f32 v[178:179], v[114:115], v[114:115]
	v_pk_mul_f32 v[184:185], v[104:105], v[104:105]
	v_pk_mov_b32 v[180:181], v[178:179], v[176:177] op_sel:[1,0]
	v_mov_b32_e32 v179, v177
	v_pk_add_f32 v[176:177], v[180:181], v[178:179]
	v_pk_mul_f32 v[178:179], v[112:113], v[112:113]
	v_pk_mul_f32 v[180:181], v[110:111], v[110:111]
	v_pk_add_f32 v[176:177], v[176:177], v[176:177] op_sel_hi:[0,1]
	v_pk_mov_b32 v[182:183], v[180:181], v[178:179] op_sel:[1,0]
	v_mov_b32_e32 v181, v179
	v_pk_add_f32 v[178:179], v[182:183], v[180:181]
	v_pk_mul_f32 v[180:181], v[108:109], v[108:109]
	v_pk_add_f32 v[178:179], v[178:179], v[178:179] op_sel_hi:[0,1]
	v_pk_mul_f32 v[182:183], v[106:107], v[106:107]
	v_pk_mul_f32 v[186:187], v[102:103], v[102:103]
	v_add_f32_e32 v183, v182, v183
	v_add_f32_e32 v181, v180, v181
	v_mov_b32_e32 v182, v186
	v_mov_b32_e32 v180, v187
	v_mov_b32_e32 v178, v184
	v_mov_b32_e32 v176, v185
	v_pk_add_f32 v[180:181], v[182:183], v[180:181]
	v_pk_add_f32 v[176:177], v[178:179], v[176:177]
	v_lshl_or_b32 v118, s2, 6, v148
	v_pk_add_f32 v[176:177], v[180:181], v[176:177]
	v_mov_b64_e32 v[120:121], s[12:13]
	v_add_f32_e32 v0, v176, v177
	ds_bpermute_b32 v178, v175, v0
	v_ashrrev_i32_e32 v119, 31, v118
	v_mad_i64_i32 v[120:121], s[0:1], v173, s80, v[120:121]
	v_lshl_add_u64 v[180:181], v[118:119], 1, v[120:121]
	s_waitcnt lgkmcnt(0)
	v_add_f32_e32 v0, v0, v178
	ds_bpermute_b32 v121, v174, v0
	v_cvt_pk_bf16_f32 v176, v132, v133
	v_cvt_pk_bf16_f32 v177, v130, v131
	v_cvt_pk_bf16_f32 v178, v128, v129
	v_cvt_pk_bf16_f32 v179, v126, v127
	s_waitcnt lgkmcnt(0)
;     __device__ __forceinline__ void operator()(const f32x4 (&acc)[2][2][4][2], const Unit& u, int wr, int wc, int fr, int fq) const {
;     ...
;                 for (int m = 0; m < 4; ++m) {
;                     const int row = row0 + ai * HALF + m * 16;
;                     const int w = row >= RPB ? row - RPB : row;
;                     f32x4 x[2][2]; float ss = 0.f;
; #pragma unroll
;                     for (int bj = 0; bj < 2; ++bj)
; #pragma unroll
;                         for (int n = 0; n < 2; ++n) { x[bj][n] = acc[ai][bj][m][n]; const f32x4 q = x[bj][n] * x[bj][n]; ss += (q[0] + q[1]) + (q[2] + q[3]); }
;                     ss += __shfl_xor(ss, 16); ss += __shfl_xor(ss, 32);
;                     const float rinv = 1.0f / sqrtf(ss * (1.0f / 64.0f) + LN_EPS);
; #pragma unroll
;                     for (int bj = 0; bj < 2; ++bj)
; #pragma unroll
;                         for (int n = 0; n < 2; ++n) x[bj][n] = x[bj][n] * rinv * gv[bj][n];
;                     if (w < SEQ) {
; #pragma unroll
;                         for (int bj = 0; bj < 2; ++bj) {
;                             const int pos = bj ? (w & 63) : (w >> 6);
; #pragma unroll
;                             for (int n = 0; n < 2; ++n) {
;                                 const f32x4 cs = *(const f32x4*)(tcos + pos * 16 + 8 * (fq & 1) + 4 * n);
;                                 const f32x4 sn = *(const f32x4*)(tsin + pos * 16 + 8 * (fq & 1) + 4 * n);
;                                 f32x4 p; p[0] = __shfl_xor(x[bj][n][0], 32); p[1] = __shfl_xor(x[bj][n][1], 32); p[2] = __shfl_xor(x[bj][n][2], 32); p[3] = __shfl_xor(x[bj][n][3], 32);
;                                 const f32x4 sgn = (fq < 2) ? -sn : sn;
;                                 x[bj][n] = x[bj][n] * cs + p * sgn;
;                             }
;                         }
;                     }
;                     bf16_t* rowp = O + (size_t)row * DIN + ocol;
; #pragma unroll
;                     for (int bj = 0; bj < 2; ++bj) { u32x4 wv; wv.x = cvt_pk_bf16(x[bj][0][0], x[bj][0][1]); wv.y = cvt_pk_bf16(x[bj][0][2], x[bj][0][3]); wv.z = cvt_pk_bf16(x[bj][1][0], x[bj][1][1]); wv.w = cvt_pk_bf16(x[bj][1][2], x[bj][1][3]);
;                         *(u32x4*)(rowp + 32 * bj) = wv; }
	v_add_f32_e32 v0, v0, v121
	v_fmamk_f32 v0, v0, 0x3c800000, v216
	v_mul_f32_e32 v121, 0x4f800000, v0
	v_cmp_gt_f32_e32 vcc, s69, v0
	flat_store_dwordx4 v[180:181], v[176:179]
	v_cvt_pk_bf16_f32 v120, v168, v169
	v_add_u32_e32 v127, 0xffffdf10, v173
	v_cndmask_b32_e32 v0, v0, v121, vcc
	v_sqrt_f32_e32 v126, v0
	v_cvt_pk_bf16_f32 v121, v122, v123
	v_cvt_pk_bf16_f32 v122, v166, v167
	v_cvt_pk_bf16_f32 v123, v124, v125
	flat_store_dwordx4 v[180:181], v[120:123] offset:64
	v_add_u32_e32 v124, -1, v126
	v_fma_f32 v125, -v124, v126, v0
	v_cmp_ge_f32_e64 s[0:1], 0, v125
	v_add_u32_e32 v125, 1, v126
	s_nop 0
	v_cndmask_b32_e64 v124, v126, v124, s[0:1]
	v_fma_f32 v126, -v125, v126, v0
	v_cmp_lt_f32_e64 s[0:1], 0, v126
	s_nop 1
	v_cndmask_b32_e64 v124, v124, v125, s[0:1]
	v_mul_f32_e32 v125, 0x37800000, v124
	v_cndmask_b32_e32 v124, v124, v125, vcc
	v_cmp_class_f32_e32 vcc, v0, v217
	s_nop 1
	v_cndmask_b32_e32 v0, v124, v0, vcc
	v_div_scale_f32 v125, s[0:1], v0, v0, 1.0
	v_rcp_f32_e32 v126, v125
	v_or_b32_e32 v124, 16, v173
	v_fma_f32 v120, -v125, v126, 1.0
	v_fmac_f32_e32 v126, v120, v126
	v_div_scale_f32 v120, vcc, 1.0, v0, 1.0
	v_mul_f32_e32 v121, v120, v126
	v_fma_f32 v122, -v125, v121, v120
	v_fmac_f32_e32 v121, v122, v126
	v_fma_f32 v120, -v125, v121, v120
	v_div_fmas_f32 v120, v120, v126, v121
	v_div_fixup_f32 v0, v120, v0, 1.0
	v_pk_mul_f32 v[120:121], v[114:115], v[0:1] op_sel_hi:[1,0]
	v_pk_mul_f32 v[114:115], v[116:117], v[0:1] op_sel_hi:[1,0]
	v_pk_mul_f32 v[116:117], v[164:165], v[120:121]
	v_pk_mul_f32 v[120:121], v[110:111], v[0:1] op_sel_hi:[1,0]
	v_cmp_lt_i32_e32 vcc, s67, v124
	v_pk_mul_f32 v[110:111], v[112:113], v[0:1] op_sel_hi:[1,0]
	v_pk_mul_f32 v[112:113], v[160:161], v[120:121]
	v_pk_mul_f32 v[120:121], v[106:107], v[0:1] op_sel_hi:[1,0]
	v_pk_mul_f32 v[106:107], v[108:109], v[0:1] op_sel_hi:[1,0]
	v_pk_mul_f32 v[102:103], v[102:103], v[0:1] op_sel_hi:[1,0]
	v_pk_mul_f32 v[104:105], v[104:105], v[0:1] op_sel_hi:[1,0]
	v_cndmask_b32_e32 v0, v124, v127, vcc
	v_pk_mul_f32 v[114:115], v[162:163], v[114:115]
	v_pk_mul_f32 v[110:111], v[158:159], v[110:111]
	v_pk_mul_f32 v[106:107], v[138:139], v[106:107]
	v_pk_mul_f32 v[120:121], v[140:141], v[120:121]
	v_pk_mul_f32 v[108:109], v[134:135], v[104:105]
	v_pk_mul_f32 v[122:123], v[136:137], v[102:103]
	v_cmp_gt_i32_e32 vcc, s66, v0
	s_and_saveexec_b64 s[0:1], vcc
	s_cbranch_execz .LBB0_262
	v_ashrrev_i32_e32 v102, 2, v0
	v_and_b32_e32 v102, -16, v102
	v_ashrrev_i32_e32 v103, 31, v102
	v_lshlrev_b64 v[102:103], 2, v[102:103]
	v_lshl_add_u64 v[130:131], v[150:151], 0, v[102:103]
	v_lshl_add_u64 v[132:133], v[152:153], 0, v[102:103]
	flat_load_dwordx4 v[102:105], v[130:131]
	flat_load_dwordx4 v[126:129], v[132:133]
	flat_load_dwordx4 v[240:243], v[130:131] offset:16
	flat_load_dwordx4 v[244:247], v[132:133] offset:16
	ds_bpermute_b32 v166, v174, v116
	ds_bpermute_b32 v167, v174, v117
	ds_bpermute_b32 v168, v174, v114
	ds_bpermute_b32 v169, v174, v115
	v_lshlrev_b32_e32 v0, 6, v0
	v_and_b32_e32 v0, 0x7c0, v0
	s_waitcnt vmcnt(0) lgkmcnt(0)
	v_xor_b32_e32 v125, 0x80000000, v126
	v_xor_b32_e32 v176, 0x80000000, v127
	v_xor_b32_e32 v177, 0x80000000, v128
	v_xor_b32_e32 v178, 0x80000000, v129
	v_cndmask_b32_e64 v129, v129, v178, s[4:5]
	v_cndmask_b32_e64 v128, v128, v177, s[4:5]
	v_cndmask_b32_e64 v127, v127, v176, s[4:5]
	v_cndmask_b32_e64 v126, v126, v125, s[4:5]
	v_pk_mul_f32 v[126:127], v[126:127], v[166:167]
	v_pk_mul_f32 v[128:129], v[128:129], v[168:169]
	v_pk_fma_f32 v[116:117], v[116:117], v[102:103], v[126:127]
	v_pk_fma_f32 v[114:115], v[114:115], v[104:105], v[128:129]
	ds_bpermute_b32 v130, v174, v112
	ds_bpermute_b32 v131, v174, v113
	ds_bpermute_b32 v132, v174, v110
	ds_bpermute_b32 v133, v174, v111
	ds_bpermute_b32 v169, v174, v107
	s_waitcnt vmcnt(0) lgkmcnt(0)
	v_xor_b32_e32 v125, 0x80000000, v244
	v_xor_b32_e32 v166, 0x80000000, v245
	v_xor_b32_e32 v167, 0x80000000, v246
	v_xor_b32_e32 v168, 0x80000000, v247
	v_cndmask_b32_e64 v247, v247, v168, s[4:5]
	v_cndmask_b32_e64 v246, v246, v167, s[4:5]
	v_cndmask_b32_e64 v245, v245, v166, s[4:5]
	v_cndmask_b32_e64 v244, v244, v125, s[4:5]
	v_pk_mul_f32 v[244:245], v[244:245], v[130:131]
	v_pk_mul_f32 v[246:247], v[246:247], v[132:133]
	v_lshl_add_u64 v[130:131], v[150:151], 0, v[0:1]
	v_pk_fma_f32 v[110:111], v[110:111], v[242:243], v[246:247]
	v_pk_fma_f32 v[112:113], v[112:113], v[240:241], v[244:245]
	v_lshl_add_u64 v[132:133], v[152:153], 0, v[0:1]
	flat_load_dwordx4 v[102:105], v[130:131]
	flat_load_dwordx4 v[126:129], v[132:133]
	flat_load_dwordx4 v[240:243], v[130:131] offset:16
	flat_load_dwordx4 v[244:247], v[132:133] offset:16
	ds_bpermute_b32 v166, v174, v120
	ds_bpermute_b32 v167, v174, v121
	ds_bpermute_b32 v168, v174, v106
	s_waitcnt vmcnt(0) lgkmcnt(0)
	v_xor_b32_e32 v0, 0x80000000, v126
	v_xor_b32_e32 v125, 0x80000000, v127
	v_xor_b32_e32 v176, 0x80000000, v128
	v_xor_b32_e32 v177, 0x80000000, v129
	v_cndmask_b32_e64 v129, v129, v177, s[4:5]
	v_cndmask_b32_e64 v128, v128, v176, s[4:5]
	v_cndmask_b32_e64 v127, v127, v125, s[4:5]
	v_cndmask_b32_e64 v126, v126, v0, s[4:5]
	v_pk_mul_f32 v[126:127], v[126:127], v[166:167]
	v_pk_mul_f32 v[128:129], v[128:129], v[168:169]
	v_pk_fma_f32 v[120:121], v[120:121], v[102:103], v[126:127]
	v_pk_fma_f32 v[106:107], v[106:107], v[104:105], v[128:129]
	ds_bpermute_b32 v130, v174, v122
	ds_bpermute_b32 v131, v174, v123
	ds_bpermute_b32 v132, v174, v108
	ds_bpermute_b32 v133, v174, v109
	s_waitcnt vmcnt(0) lgkmcnt(0)
	v_xor_b32_e32 v0, 0x80000000, v244
	v_xor_b32_e32 v125, 0x80000000, v245
	v_xor_b32_e32 v166, 0x80000000, v246
	v_xor_b32_e32 v167, 0x80000000, v247
	v_cndmask_b32_e64 v247, v247, v167, s[4:5]
	v_cndmask_b32_e64 v246, v246, v166, s[4:5]
	v_cndmask_b32_e64 v245, v245, v125, s[4:5]
	v_cndmask_b32_e64 v244, v244, v0, s[4:5]
	v_pk_mul_f32 v[244:245], v[244:245], v[130:131]
	v_pk_mul_f32 v[246:247], v[246:247], v[132:133]
	v_pk_fma_f32 v[122:123], v[122:123], v[240:241], v[244:245]
	v_pk_fma_f32 v[108:109], v[108:109], v[242:243], v[246:247]
;     __device__ __forceinline__ void operator()(const f32x4 (&acc)[2][2][4][2], const Unit& u, int wr, int wc, int fr, int fq) const {
;     ...
;                 for (int m = 0; m < 4; ++m) {
;                     const int row = row0 + ai * HALF + m * 16;
;                     const int w = row >= RPB ? row - RPB : row;
;                     f32x4 x[2][2]; float ss = 0.f;
; #pragma unroll
;                     for (int bj = 0; bj < 2; ++bj)
; #pragma unroll
;                         for (int n = 0; n < 2; ++n) { x[bj][n] = acc[ai][bj][m][n]; const f32x4 q = x[bj][n] * x[bj][n]; ss += (q[0] + q[1]) + (q[2] + q[3]); }
;                     ss += __shfl_xor(ss, 16); ss += __shfl_xor(ss, 32);
;                     const float rinv = 1.0f / sqrtf(ss * (1.0f / 64.0f) + LN_EPS);
; #pragma unroll
;                     for (int bj = 0; bj < 2; ++bj)
; #pragma unroll
;                         for (int n = 0; n < 2; ++n) x[bj][n] = x[bj][n] * rinv * gv[bj][n];
;                     if (w < SEQ) {
; #pragma unroll
;                         for (int bj = 0; bj < 2; ++bj) {
;                             const int pos = bj ? (w & 63) : (w >> 6);
; #pragma unroll
;                             for (int n = 0; n < 2; ++n) {
;                                 const f32x4 cs = *(const f32x4*)(tcos + pos * 16 + 8 * (fq & 1) + 4 * n);
;                                 const f32x4 sn = *(const f32x4*)(tsin + pos * 16 + 8 * (fq & 1) + 4 * n);
;                                 f32x4 p; p[0] = __shfl_xor(x[bj][n][0], 32); p[1] = __shfl_xor(x[bj][n][1], 32); p[2] = __shfl_xor(x[bj][n][2], 32); p[3] = __shfl_xor(x[bj][n][3], 32);
;                                 const f32x4 sgn = (fq < 2) ? -sn : sn;
;                                 x[bj][n] = x[bj][n] * cs + p * sgn;
;                             }
;                         }
;                     }
;                     bf16_t* rowp = O + (size_t)row * DIN + ocol;
; #pragma unroll
;                     for (int bj = 0; bj < 2; ++bj) { u32x4 wv; wv.x = cvt_pk_bf16(x[bj][0][0], x[bj][0][1]); wv.y = cvt_pk_bf16(x[bj][0][2], x[bj][0][3]); wv.z = cvt_pk_bf16(x[bj][1][0], x[bj][1][1]); wv.w = cvt_pk_bf16(x[bj][1][2], x[bj][1][3]);
;                         *(u32x4*)(rowp + 32 * bj) = wv; }
.LBB0_262:
	s_or_b64 exec, exec, s[0:1]
	v_pk_mul_f32 v[104:105], v[100:101], v[100:101]
	v_pk_mul_f32 v[126:127], v[98:99], v[98:99]
	v_pk_mul_f32 v[132:133], v[88:89], v[88:89]
	v_pk_mov_b32 v[128:129], v[126:127], v[104:105] op_sel:[1,0]
	v_mov_b32_e32 v127, v105
	v_pk_add_f32 v[104:105], v[128:129], v[126:127]
	v_pk_mul_f32 v[126:127], v[96:97], v[96:97]
	v_pk_mul_f32 v[128:129], v[94:95], v[94:95]
	v_pk_add_f32 v[104:105], v[104:105], v[104:105] op_sel_hi:[0,1]
	v_pk_mov_b32 v[130:131], v[128:129], v[126:127] op_sel:[1,0]
	v_mov_b32_e32 v129, v127
	v_pk_add_f32 v[126:127], v[130:131], v[128:129]
	v_pk_mul_f32 v[128:129], v[92:93], v[92:93]
	v_pk_add_f32 v[126:127], v[126:127], v[126:127] op_sel_hi:[0,1]
	v_pk_mul_f32 v[130:131], v[90:91], v[90:91]
	v_pk_mul_f32 v[166:167], v[86:87], v[86:87]
	v_add_f32_e32 v131, v130, v131
	v_add_f32_e32 v129, v128, v129
	v_mov_b32_e32 v130, v166
	v_mov_b32_e32 v128, v167
	v_mov_b32_e32 v126, v132
	v_mov_b32_e32 v104, v133
	v_pk_add_f32 v[128:129], v[130:131], v[128:129]
	v_pk_add_f32 v[104:105], v[126:127], v[104:105]
	v_mov_b64_e32 v[102:103], s[12:13]
	v_pk_add_f32 v[104:105], v[128:129], v[104:105]
	v_mad_i64_i32 v[102:103], s[0:1], v124, s80, v[102:103]
	v_add_f32_e32 v0, v104, v105
	ds_bpermute_b32 v104, v175, v0
	v_lshl_add_u64 v[124:125], v[118:119], 1, v[102:103]
	v_cvt_pk_bf16_f32 v102, v116, v117
	v_cvt_pk_bf16_f32 v103, v114, v115
	s_waitcnt lgkmcnt(0)
	v_add_f32_e32 v0, v0, v104
	ds_bpermute_b32 v114, v174, v0
	v_cvt_pk_bf16_f32 v104, v112, v113
	v_cvt_pk_bf16_f32 v105, v110, v111
	flat_store_dwordx4 v[124:125], v[102:105]
	s_waitcnt lgkmcnt(0)
	v_add_f32_e32 v0, v0, v114
	v_fmamk_f32 v0, v0, 0x3c800000, v216
	v_mul_f32_e32 v103, 0x4f800000, v0
	v_cmp_gt_f32_e32 vcc, s69, v0
	v_cvt_pk_bf16_f32 v102, v120, v121
	s_nop 1
	v_cndmask_b32_e32 v0, v0, v103, vcc
	v_sqrt_f32_e32 v110, v0
	v_cvt_pk_bf16_f32 v103, v106, v107
	v_cvt_pk_bf16_f32 v104, v122, v123
	v_cvt_pk_bf16_f32 v105, v108, v109
	flat_store_dwordx4 v[124:125], v[102:105] offset:64
	v_add_u32_e32 v106, -1, v110
	v_fma_f32 v107, -v106, v110, v0
	v_cmp_ge_f32_e64 s[0:1], 0, v107
	v_add_u32_e32 v107, 1, v110
	v_fma_f32 v108, -v107, v110, v0
	v_cndmask_b32_e64 v106, v110, v106, s[0:1]
	v_cmp_lt_f32_e64 s[0:1], 0, v108
	v_add_u32_e32 v109, 0xffffdf20, v173
	s_nop 0
	v_cndmask_b32_e64 v106, v106, v107, s[0:1]
	v_mul_f32_e32 v107, 0x37800000, v106
	v_cndmask_b32_e32 v106, v106, v107, vcc
	v_cmp_class_f32_e32 vcc, v0, v217
	s_nop 1
	v_cndmask_b32_e32 v0, v106, v0, vcc
	v_div_scale_f32 v107, s[0:1], v0, v0, 1.0
	v_rcp_f32_e32 v108, v107
	v_or_b32_e32 v106, 32, v173
	v_fma_f32 v102, -v107, v108, 1.0
	v_fmac_f32_e32 v108, v102, v108
	v_div_scale_f32 v102, vcc, 1.0, v0, 1.0
	v_mul_f32_e32 v103, v102, v108
	v_fma_f32 v104, -v107, v103, v102
	v_fmac_f32_e32 v103, v104, v108
	v_fma_f32 v102, -v107, v103, v102
	v_div_fmas_f32 v102, v102, v108, v103
	v_div_fixup_f32 v0, v102, v0, 1.0
	v_pk_mul_f32 v[102:103], v[98:99], v[0:1] op_sel_hi:[1,0]
	v_pk_mul_f32 v[98:99], v[100:101], v[0:1] op_sel_hi:[1,0]
	v_pk_mul_f32 v[100:101], v[164:165], v[102:103]
	v_pk_mul_f32 v[102:103], v[94:95], v[0:1] op_sel_hi:[1,0]
	v_cmp_lt_i32_e32 vcc, s67, v106
	v_pk_mul_f32 v[94:95], v[96:97], v[0:1] op_sel_hi:[1,0]
	v_pk_mul_f32 v[96:97], v[160:161], v[102:103]
	v_pk_mul_f32 v[102:103], v[90:91], v[0:1] op_sel_hi:[1,0]
	v_pk_mul_f32 v[90:91], v[92:93], v[0:1] op_sel_hi:[1,0]
	v_pk_mul_f32 v[86:87], v[86:87], v[0:1] op_sel_hi:[1,0]
	v_pk_mul_f32 v[88:89], v[88:89], v[0:1] op_sel_hi:[1,0]
	v_cndmask_b32_e32 v0, v106, v109, vcc
	v_pk_mul_f32 v[98:99], v[162:163], v[98:99]
	v_pk_mul_f32 v[94:95], v[158:159], v[94:95]
	v_pk_mul_f32 v[90:91], v[138:139], v[90:91]
	v_pk_mul_f32 v[104:105], v[140:141], v[102:103]
	v_pk_mul_f32 v[92:93], v[134:135], v[88:89]
	v_pk_mul_f32 v[102:103], v[136:137], v[86:87]
	v_cmp_gt_i32_e32 vcc, s66, v0
	s_and_saveexec_b64 s[0:1], vcc
	s_cbranch_execz .LBB0_264
	v_ashrrev_i32_e32 v86, 2, v0
	v_and_b32_e32 v86, -16, v86
	v_ashrrev_i32_e32 v87, 31, v86
	v_lshlrev_b64 v[86:87], 2, v[86:87]
	v_lshl_add_u64 v[112:113], v[150:151], 0, v[86:87]
	v_lshl_add_u64 v[114:115], v[152:153], 0, v[86:87]
	flat_load_dwordx4 v[86:89], v[112:113]
	flat_load_dwordx4 v[108:111], v[114:115]
	flat_load_dwordx4 v[240:243], v[112:113] offset:16
	flat_load_dwordx4 v[244:247], v[114:115] offset:16
	ds_bpermute_b32 v116, v174, v100
	ds_bpermute_b32 v117, v174, v101
	ds_bpermute_b32 v120, v174, v98
	ds_bpermute_b32 v121, v174, v99
	v_lshlrev_b32_e32 v0, 6, v0
	v_and_b32_e32 v0, 0xbc0, v0
	s_waitcnt vmcnt(0) lgkmcnt(0)
	v_xor_b32_e32 v107, 0x80000000, v108
	v_xor_b32_e32 v122, 0x80000000, v109
	v_xor_b32_e32 v123, 0x80000000, v110
	v_xor_b32_e32 v124, 0x80000000, v111
	v_cndmask_b32_e64 v111, v111, v124, s[4:5]
	v_cndmask_b32_e64 v110, v110, v123, s[4:5]
	v_cndmask_b32_e64 v109, v109, v122, s[4:5]
	v_cndmask_b32_e64 v108, v108, v107, s[4:5]
	v_pk_mul_f32 v[108:109], v[108:109], v[116:117]
	v_pk_mul_f32 v[110:111], v[110:111], v[120:121]
	v_pk_fma_f32 v[100:101], v[100:101], v[86:87], v[108:109]
	v_pk_fma_f32 v[98:99], v[98:99], v[88:89], v[110:111]
	ds_bpermute_b32 v112, v174, v96
	ds_bpermute_b32 v113, v174, v97
	ds_bpermute_b32 v114, v174, v94
	ds_bpermute_b32 v115, v174, v95
	ds_bpermute_b32 v121, v174, v91
	s_waitcnt vmcnt(0) lgkmcnt(0)
;     __device__ __forceinline__ void operator()(const f32x4 (&acc)[2][2][4][2], const Unit& u, int wr, int wc, int fr, int fq) const {
;     ...
;                 for (int m = 0; m < 4; ++m) {
;                     const int row = row0 + ai * HALF + m * 16;
;                     const int w = row >= RPB ? row - RPB : row;
;                     f32x4 x[2][2]; float ss = 0.f;
; #pragma unroll
;                     for (int bj = 0; bj < 2; ++bj)
; #pragma unroll
;                         for (int n = 0; n < 2; ++n) { x[bj][n] = acc[ai][bj][m][n]; const f32x4 q = x[bj][n] * x[bj][n]; ss += (q[0] + q[1]) + (q[2] + q[3]); }
;                     ss += __shfl_xor(ss, 16); ss += __shfl_xor(ss, 32);
;                     const float rinv = 1.0f / sqrtf(ss * (1.0f / 64.0f) + LN_EPS);
; #pragma unroll
;                     for (int bj = 0; bj < 2; ++bj)
; #pragma unroll
;                         for (int n = 0; n < 2; ++n) x[bj][n] = x[bj][n] * rinv * gv[bj][n];
;                     if (w < SEQ) {
; #pragma unroll
;                         for (int bj = 0; bj < 2; ++bj) {
;                             const int pos = bj ? (w & 63) : (w >> 6);
; #pragma unroll
;                             for (int n = 0; n < 2; ++n) {
;                                 const f32x4 cs = *(const f32x4*)(tcos + pos * 16 + 8 * (fq & 1) + 4 * n);
;                                 const f32x4 sn = *(const f32x4*)(tsin + pos * 16 + 8 * (fq & 1) + 4 * n);
;                                 f32x4 p; p[0] = __shfl_xor(x[bj][n][0], 32); p[1] = __shfl_xor(x[bj][n][1], 32); p[2] = __shfl_xor(x[bj][n][2], 32); p[3] = __shfl_xor(x[bj][n][3], 32);
;                                 const f32x4 sgn = (fq < 2) ? -sn : sn;
;                                 x[bj][n] = x[bj][n] * cs + p * sgn;
;                             }
;                         }
;                     }
;                     bf16_t* rowp = O + (size_t)row * DIN + ocol;
; #pragma unroll
;                     for (int bj = 0; bj < 2; ++bj) { u32x4 wv; wv.x = cvt_pk_bf16(x[bj][0][0], x[bj][0][1]); wv.y = cvt_pk_bf16(x[bj][0][2], x[bj][0][3]); wv.z = cvt_pk_bf16(x[bj][1][0], x[bj][1][1]); wv.w = cvt_pk_bf16(x[bj][1][2], x[bj][1][3]);
;                         *(u32x4*)(rowp + 32 * bj) = wv; }
	v_xor_b32_e32 v107, 0x80000000, v244
	v_xor_b32_e32 v116, 0x80000000, v245
	v_xor_b32_e32 v117, 0x80000000, v246
	v_xor_b32_e32 v120, 0x80000000, v247
	v_cndmask_b32_e64 v247, v247, v120, s[4:5]
	v_cndmask_b32_e64 v246, v246, v117, s[4:5]
	v_cndmask_b32_e64 v245, v245, v116, s[4:5]
	v_cndmask_b32_e64 v244, v244, v107, s[4:5]
	v_pk_mul_f32 v[244:245], v[244:245], v[112:113]
	v_pk_mul_f32 v[246:247], v[246:247], v[114:115]
	v_lshl_add_u64 v[112:113], v[150:151], 0, v[0:1]
	v_pk_fma_f32 v[94:95], v[94:95], v[242:243], v[246:247]
	v_pk_fma_f32 v[96:97], v[96:97], v[240:241], v[244:245]
	v_lshl_add_u64 v[114:115], v[152:153], 0, v[0:1]
	flat_load_dwordx4 v[86:89], v[112:113]
	flat_load_dwordx4 v[108:111], v[114:115]
	flat_load_dwordx4 v[240:243], v[112:113] offset:16
	flat_load_dwordx4 v[244:247], v[114:115] offset:16
	ds_bpermute_b32 v116, v174, v104
	ds_bpermute_b32 v117, v174, v105
	ds_bpermute_b32 v120, v174, v90
	s_waitcnt vmcnt(0) lgkmcnt(0)
	v_xor_b32_e32 v0, 0x80000000, v108
	v_xor_b32_e32 v107, 0x80000000, v109
	v_xor_b32_e32 v122, 0x80000000, v110
	v_xor_b32_e32 v123, 0x80000000, v111
	v_cndmask_b32_e64 v111, v111, v123, s[4:5]
	v_cndmask_b32_e64 v110, v110, v122, s[4:5]
	v_cndmask_b32_e64 v109, v109, v107, s[4:5]
	v_cndmask_b32_e64 v108, v108, v0, s[4:5]
	v_pk_mul_f32 v[108:109], v[108:109], v[116:117]
	v_pk_mul_f32 v[110:111], v[110:111], v[120:121]
	v_pk_fma_f32 v[104:105], v[104:105], v[86:87], v[108:109]
	v_pk_fma_f32 v[90:91], v[90:91], v[88:89], v[110:111]
	ds_bpermute_b32 v112, v174, v102
	ds_bpermute_b32 v113, v174, v103
	ds_bpermute_b32 v114, v174, v92
	ds_bpermute_b32 v115, v174, v93
	s_waitcnt vmcnt(0) lgkmcnt(0)
	v_xor_b32_e32 v0, 0x80000000, v244
	v_xor_b32_e32 v107, 0x80000000, v245
	v_xor_b32_e32 v116, 0x80000000, v246
	v_xor_b32_e32 v117, 0x80000000, v247
	v_cndmask_b32_e64 v247, v247, v117, s[4:5]
	v_cndmask_b32_e64 v246, v246, v116, s[4:5]
	v_cndmask_b32_e64 v245, v245, v107, s[4:5]
	v_cndmask_b32_e64 v244, v244, v0, s[4:5]
	v_pk_mul_f32 v[244:245], v[244:245], v[112:113]
	v_pk_mul_f32 v[246:247], v[246:247], v[114:115]
	v_pk_fma_f32 v[102:103], v[102:103], v[240:241], v[244:245]
	v_pk_fma_f32 v[92:93], v[92:93], v[242:243], v[246:247]
.LBB0_264:
	s_or_b64 exec, exec, s[0:1]
	v_pk_mul_f32 v[88:89], v[84:85], v[84:85]
	v_pk_mul_f32 v[108:109], v[82:83], v[82:83]
	v_pk_mul_f32 v[114:115], v[72:73], v[72:73]
	v_pk_mov_b32 v[110:111], v[108:109], v[88:89] op_sel:[1,0]
	v_mov_b32_e32 v109, v89
	v_pk_add_f32 v[88:89], v[110:111], v[108:109]
	v_pk_mul_f32 v[108:109], v[80:81], v[80:81]
	v_pk_mul_f32 v[110:111], v[78:79], v[78:79]
	v_pk_add_f32 v[88:89], v[88:89], v[88:89] op_sel_hi:[0,1]
	v_pk_mov_b32 v[112:113], v[110:111], v[108:109] op_sel:[1,0]
	v_mov_b32_e32 v111, v109
	v_pk_add_f32 v[108:109], v[112:113], v[110:111]
	v_pk_mul_f32 v[110:111], v[76:77], v[76:77]
	v_pk_add_f32 v[108:109], v[108:109], v[108:109] op_sel_hi:[0,1]
	v_pk_mul_f32 v[112:113], v[74:75], v[74:75]
	v_pk_mul_f32 v[116:117], v[70:71], v[70:71]
	v_add_f32_e32 v113, v112, v113
	v_add_f32_e32 v111, v110, v111
	v_mov_b32_e32 v112, v116
	v_mov_b32_e32 v110, v117
	v_mov_b32_e32 v108, v114
	v_mov_b32_e32 v88, v115
	v_pk_add_f32 v[110:111], v[112:113], v[110:111]
	v_pk_add_f32 v[88:89], v[108:109], v[88:89]
	v_mov_b64_e32 v[86:87], s[12:13]
	v_pk_add_f32 v[88:89], v[110:111], v[88:89]
	v_mad_i64_i32 v[86:87], s[0:1], v106, s80, v[86:87]
	v_add_f32_e32 v0, v88, v89
	ds_bpermute_b32 v88, v175, v0
	v_lshl_add_u64 v[106:107], v[118:119], 1, v[86:87]
	v_cvt_pk_bf16_f32 v86, v100, v101
	v_cvt_pk_bf16_f32 v87, v98, v99
	s_waitcnt lgkmcnt(0)
	v_add_f32_e32 v0, v0, v88
	ds_bpermute_b32 v98, v174, v0
	v_cvt_pk_bf16_f32 v88, v96, v97
	v_cvt_pk_bf16_f32 v89, v94, v95
	flat_store_dwordx4 v[106:107], v[86:89]
	s_waitcnt lgkmcnt(0)
	v_add_f32_e32 v0, v0, v98
	v_fmamk_f32 v0, v0, 0x3c800000, v216
	v_mul_f32_e32 v87, 0x4f800000, v0
	v_cmp_gt_f32_e32 vcc, s69, v0
	v_cvt_pk_bf16_f32 v86, v104, v105
	s_nop 1
	v_cndmask_b32_e32 v0, v0, v87, vcc
	v_sqrt_f32_e32 v94, v0
	v_cvt_pk_bf16_f32 v87, v90, v91
	v_cvt_pk_bf16_f32 v88, v102, v103
	v_cvt_pk_bf16_f32 v89, v92, v93
	flat_store_dwordx4 v[106:107], v[86:89] offset:64
	v_add_u32_e32 v90, -1, v94
	v_fma_f32 v91, -v90, v94, v0
	v_cmp_ge_f32_e64 s[0:1], 0, v91
	v_add_u32_e32 v91, 1, v94
	v_fma_f32 v92, -v91, v94, v0
	v_cndmask_b32_e64 v90, v94, v90, s[0:1]
	v_cmp_lt_f32_e64 s[0:1], 0, v92
	v_add_u32_e32 v93, 0xffffdf30, v173
	s_nop 0
	v_cndmask_b32_e64 v90, v90, v91, s[0:1]
	v_mul_f32_e32 v91, 0x37800000, v90
	v_cndmask_b32_e32 v90, v90, v91, vcc
	v_cmp_class_f32_e32 vcc, v0, v217
	s_nop 1
	v_cndmask_b32_e32 v0, v90, v0, vcc
	v_div_scale_f32 v91, s[0:1], v0, v0, 1.0
	v_rcp_f32_e32 v92, v91
	v_or_b32_e32 v90, 48, v173
	v_fma_f32 v86, -v91, v92, 1.0
	v_fmac_f32_e32 v92, v86, v92
	v_div_scale_f32 v86, vcc, 1.0, v0, 1.0
	v_mul_f32_e32 v87, v86, v92
	v_fma_f32 v88, -v91, v87, v86
	v_fmac_f32_e32 v87, v88, v92
	v_fma_f32 v86, -v91, v87, v86
	v_div_fmas_f32 v86, v86, v92, v87
	v_div_fixup_f32 v0, v86, v0, 1.0
	v_pk_mul_f32 v[86:87], v[82:83], v[0:1] op_sel_hi:[1,0]
	v_pk_mul_f32 v[82:83], v[84:85], v[0:1] op_sel_hi:[1,0]
	v_pk_mul_f32 v[84:85], v[164:165], v[86:87]
	v_pk_mul_f32 v[86:87], v[78:79], v[0:1] op_sel_hi:[1,0]
	v_cmp_lt_i32_e32 vcc, s67, v90
	v_pk_mul_f32 v[78:79], v[80:81], v[0:1] op_sel_hi:[1,0]
	v_pk_mul_f32 v[80:81], v[160:161], v[86:87]
	v_pk_mul_f32 v[86:87], v[74:75], v[0:1] op_sel_hi:[1,0]
	v_pk_mul_f32 v[74:75], v[76:77], v[0:1] op_sel_hi:[1,0]
	v_pk_mul_f32 v[70:71], v[70:71], v[0:1] op_sel_hi:[1,0]
	v_pk_mul_f32 v[72:73], v[72:73], v[0:1] op_sel_hi:[1,0]
	v_cndmask_b32_e32 v0, v90, v93, vcc
	v_pk_mul_f32 v[82:83], v[162:163], v[82:83]
	v_pk_mul_f32 v[78:79], v[158:159], v[78:79]
	v_pk_mul_f32 v[74:75], v[138:139], v[74:75]
	v_pk_mul_f32 v[86:87], v[140:141], v[86:87]
	v_pk_mul_f32 v[76:77], v[134:135], v[72:73]
	v_pk_mul_f32 v[88:89], v[136:137], v[70:71]
	v_cmp_gt_i32_e32 vcc, s66, v0
	s_and_saveexec_b64 s[0:1], vcc
	s_cbranch_execz .LBB0_266
;     __device__ __forceinline__ void operator()(const f32x4 (&acc)[2][2][4][2], const Unit& u, int wr, int wc, int fr, int fq) const {
;     ...
;                 for (int m = 0; m < 4; ++m) {
;                     const int row = row0 + ai * HALF + m * 16;
;                     const int w = row >= RPB ? row - RPB : row;
;                     f32x4 x[2][2]; float ss = 0.f;
; #pragma unroll
;                     for (int bj = 0; bj < 2; ++bj)
; #pragma unroll
;                         for (int n = 0; n < 2; ++n) { x[bj][n] = acc[ai][bj][m][n]; const f32x4 q = x[bj][n] * x[bj][n]; ss += (q[0] + q[1]) + (q[2] + q[3]); }
;                     ss += __shfl_xor(ss, 16); ss += __shfl_xor(ss, 32);
;                     const float rinv = 1.0f / sqrtf(ss * (1.0f / 64.0f) + LN_EPS);
; #pragma unroll
;                     for (int bj = 0; bj < 2; ++bj)
; #pragma unroll
;                         for (int n = 0; n < 2; ++n) x[bj][n] = x[bj][n] * rinv * gv[bj][n];
;                     if (w < SEQ) {
; #pragma unroll
;                         for (int bj = 0; bj < 2; ++bj) {
;                             const int pos = bj ? (w & 63) : (w >> 6);
; #pragma unroll
;                             for (int n = 0; n < 2; ++n) {
;                                 const f32x4 cs = *(const f32x4*)(tcos + pos * 16 + 8 * (fq & 1) + 4 * n);
;                                 const f32x4 sn = *(const f32x4*)(tsin + pos * 16 + 8 * (fq & 1) + 4 * n);
;                                 f32x4 p; p[0] = __shfl_xor(x[bj][n][0], 32); p[1] = __shfl_xor(x[bj][n][1], 32); p[2] = __shfl_xor(x[bj][n][2], 32); p[3] = __shfl_xor(x[bj][n][3], 32);
;                                 const f32x4 sgn = (fq < 2) ? -sn : sn;
;                                 x[bj][n] = x[bj][n] * cs + p * sgn;
;                             }
;                         }
;                     }
;                     bf16_t* rowp = O + (size_t)row * DIN + ocol;
; #pragma unroll
;                     for (int bj = 0; bj < 2; ++bj) { u32x4 wv; wv.x = cvt_pk_bf16(x[bj][0][0], x[bj][0][1]); wv.y = cvt_pk_bf16(x[bj][0][2], x[bj][0][3]); wv.z = cvt_pk_bf16(x[bj][1][0], x[bj][1][1]); wv.w = cvt_pk_bf16(x[bj][1][2], x[bj][1][3]);
;                         *(u32x4*)(rowp + 32 * bj) = wv; }
	v_ashrrev_i32_e32 v70, 2, v0
	v_and_b32_e32 v70, -16, v70
	v_ashrrev_i32_e32 v71, 31, v70
	v_lshlrev_b64 v[70:71], 2, v[70:71]
	v_lshl_add_u64 v[96:97], v[150:151], 0, v[70:71]
	v_lshl_add_u64 v[98:99], v[152:153], 0, v[70:71]
	flat_load_dwordx4 v[70:73], v[96:97]
	flat_load_dwordx4 v[92:95], v[98:99]
	flat_load_dwordx4 v[240:243], v[96:97] offset:16
	flat_load_dwordx4 v[244:247], v[98:99] offset:16
	ds_bpermute_b32 v100, v174, v84
	ds_bpermute_b32 v101, v174, v85
	ds_bpermute_b32 v102, v174, v82
	ds_bpermute_b32 v103, v174, v83
	v_lshlrev_b32_e32 v0, 6, v0
	v_and_b32_e32 v0, 0xfc0, v0
	s_waitcnt vmcnt(0) lgkmcnt(0)
	v_xor_b32_e32 v91, 0x80000000, v92
	v_xor_b32_e32 v104, 0x80000000, v93
	v_xor_b32_e32 v105, 0x80000000, v94
	v_xor_b32_e32 v106, 0x80000000, v95
	v_cndmask_b32_e64 v95, v95, v106, s[4:5]
	v_cndmask_b32_e64 v94, v94, v105, s[4:5]
	v_cndmask_b32_e64 v93, v93, v104, s[4:5]
	v_cndmask_b32_e64 v92, v92, v91, s[4:5]
	v_pk_mul_f32 v[92:93], v[92:93], v[100:101]
	v_pk_mul_f32 v[94:95], v[94:95], v[102:103]
	v_pk_fma_f32 v[84:85], v[84:85], v[70:71], v[92:93]
	v_pk_fma_f32 v[82:83], v[82:83], v[72:73], v[94:95]
	ds_bpermute_b32 v96, v174, v80
	ds_bpermute_b32 v97, v174, v81
	ds_bpermute_b32 v98, v174, v78
	ds_bpermute_b32 v99, v174, v79
	ds_bpermute_b32 v103, v174, v75
	s_waitcnt vmcnt(0) lgkmcnt(0)
	v_xor_b32_e32 v91, 0x80000000, v244
	v_xor_b32_e32 v100, 0x80000000, v245
	v_xor_b32_e32 v101, 0x80000000, v246
	v_xor_b32_e32 v102, 0x80000000, v247
	v_cndmask_b32_e64 v247, v247, v102, s[4:5]
	v_cndmask_b32_e64 v246, v246, v101, s[4:5]
	v_cndmask_b32_e64 v245, v245, v100, s[4:5]
	v_cndmask_b32_e64 v244, v244, v91, s[4:5]
	v_pk_mul_f32 v[244:245], v[244:245], v[96:97]
	v_pk_mul_f32 v[246:247], v[246:247], v[98:99]
	v_lshl_add_u64 v[96:97], v[150:151], 0, v[0:1]
	v_pk_fma_f32 v[78:79], v[78:79], v[242:243], v[246:247]
	v_pk_fma_f32 v[80:81], v[80:81], v[240:241], v[244:245]
	v_lshl_add_u64 v[98:99], v[152:153], 0, v[0:1]
	flat_load_dwordx4 v[70:73], v[96:97]
	flat_load_dwordx4 v[92:95], v[98:99]
	flat_load_dwordx4 v[240:243], v[96:97] offset:16
	flat_load_dwordx4 v[244:247], v[98:99] offset:16
	ds_bpermute_b32 v100, v174, v86
	ds_bpermute_b32 v101, v174, v87
	ds_bpermute_b32 v102, v174, v74
	s_waitcnt vmcnt(0) lgkmcnt(0)
	v_xor_b32_e32 v0, 0x80000000, v92
	v_xor_b32_e32 v91, 0x80000000, v93
	v_xor_b32_e32 v104, 0x80000000, v94
	v_xor_b32_e32 v105, 0x80000000, v95
	v_cndmask_b32_e64 v95, v95, v105, s[4:5]
	v_cndmask_b32_e64 v94, v94, v104, s[4:5]
	v_cndmask_b32_e64 v93, v93, v91, s[4:5]
	v_cndmask_b32_e64 v92, v92, v0, s[4:5]
	v_pk_mul_f32 v[92:93], v[92:93], v[100:101]
	v_pk_mul_f32 v[94:95], v[94:95], v[102:103]
	v_pk_fma_f32 v[86:87], v[86:87], v[70:71], v[92:93]
	v_pk_fma_f32 v[74:75], v[74:75], v[72:73], v[94:95]
	ds_bpermute_b32 v96, v174, v88
	ds_bpermute_b32 v97, v174, v89
	ds_bpermute_b32 v98, v174, v76
	ds_bpermute_b32 v99, v174, v77
	s_waitcnt vmcnt(0) lgkmcnt(0)
	v_xor_b32_e32 v0, 0x80000000, v244
	v_xor_b32_e32 v91, 0x80000000, v245
	v_xor_b32_e32 v100, 0x80000000, v246
	v_xor_b32_e32 v101, 0x80000000, v247
	v_cndmask_b32_e64 v247, v247, v101, s[4:5]
	v_cndmask_b32_e64 v246, v246, v100, s[4:5]
	v_cndmask_b32_e64 v245, v245, v91, s[4:5]
	v_cndmask_b32_e64 v244, v244, v0, s[4:5]
	v_pk_mul_f32 v[244:245], v[244:245], v[96:97]
	v_pk_mul_f32 v[246:247], v[246:247], v[98:99]
	v_pk_fma_f32 v[88:89], v[88:89], v[240:241], v[244:245]
	v_pk_fma_f32 v[76:77], v[76:77], v[242:243], v[246:247]
.LBB0_266:
	s_or_b64 exec, exec, s[0:1]
	v_pk_mul_f32 v[72:73], v[68:69], v[68:69]
	v_pk_mul_f32 v[92:93], v[66:67], v[66:67]
	v_pk_mul_f32 v[98:99], v[56:57], v[56:57]
	v_pk_mov_b32 v[94:95], v[92:93], v[72:73] op_sel:[1,0]
	v_mov_b32_e32 v93, v73
	v_pk_add_f32 v[72:73], v[94:95], v[92:93]
	v_pk_mul_f32 v[92:93], v[64:65], v[64:65]
	v_pk_mul_f32 v[94:95], v[62:63], v[62:63]
	v_pk_add_f32 v[72:73], v[72:73], v[72:73] op_sel_hi:[0,1]
	v_pk_mov_b32 v[96:97], v[94:95], v[92:93] op_sel:[1,0]
	v_mov_b32_e32 v95, v93
	v_pk_add_f32 v[92:93], v[96:97], v[94:95]
	v_pk_mul_f32 v[94:95], v[60:61], v[60:61]
	v_pk_add_f32 v[92:93], v[92:93], v[92:93] op_sel_hi:[0,1]
	v_pk_mul_f32 v[96:97], v[58:59], v[58:59]
	v_pk_mul_f32 v[100:101], v[54:55], v[54:55]
	v_add_f32_e32 v97, v96, v97
	v_add_f32_e32 v95, v94, v95
	v_mov_b32_e32 v96, v100
	v_mov_b32_e32 v94, v101
	v_mov_b32_e32 v92, v98
	v_mov_b32_e32 v72, v99
	v_pk_add_f32 v[94:95], v[96:97], v[94:95]
	v_pk_add_f32 v[72:73], v[92:93], v[72:73]
	v_mov_b64_e32 v[70:71], s[12:13]
	v_pk_add_f32 v[72:73], v[94:95], v[72:73]
	v_mad_i64_i32 v[70:71], s[0:1], v90, s80, v[70:71]
	v_add_f32_e32 v0, v72, v73
	ds_bpermute_b32 v72, v175, v0
	v_lshl_add_u64 v[90:91], v[118:119], 1, v[70:71]
	v_cvt_pk_bf16_f32 v70, v84, v85
	v_cvt_pk_bf16_f32 v71, v82, v83
	s_waitcnt lgkmcnt(0)
	v_add_f32_e32 v0, v0, v72
	ds_bpermute_b32 v82, v174, v0
	v_cvt_pk_bf16_f32 v72, v80, v81
	v_cvt_pk_bf16_f32 v73, v78, v79
	flat_store_dwordx4 v[90:91], v[70:73]
	s_waitcnt lgkmcnt(0)
;     __device__ __forceinline__ void operator()(const f32x4 (&acc)[2][2][4][2], const Unit& u, int wr, int wc, int fr, int fq) const {
;     ...
;                 for (int m = 0; m < 4; ++m) {
;                     const int row = row0 + ai * HALF + m * 16;
;                     const int w = row >= RPB ? row - RPB : row;
;                     f32x4 x[2][2]; float ss = 0.f;
; #pragma unroll
;                     for (int bj = 0; bj < 2; ++bj)
; #pragma unroll
;                         for (int n = 0; n < 2; ++n) { x[bj][n] = acc[ai][bj][m][n]; const f32x4 q = x[bj][n] * x[bj][n]; ss += (q[0] + q[1]) + (q[2] + q[3]); }
;                     ss += __shfl_xor(ss, 16); ss += __shfl_xor(ss, 32);
;                     const float rinv = 1.0f / sqrtf(ss * (1.0f / 64.0f) + LN_EPS);
; #pragma unroll
;                     for (int bj = 0; bj < 2; ++bj)
; #pragma unroll
;                         for (int n = 0; n < 2; ++n) x[bj][n] = x[bj][n] * rinv * gv[bj][n];
;                     if (w < SEQ) {
; #pragma unroll
;                         for (int bj = 0; bj < 2; ++bj) {
;                             const int pos = bj ? (w & 63) : (w >> 6);
; #pragma unroll
;                             for (int n = 0; n < 2; ++n) {
;                                 const f32x4 cs = *(const f32x4*)(tcos + pos * 16 + 8 * (fq & 1) + 4 * n);
;                                 const f32x4 sn = *(const f32x4*)(tsin + pos * 16 + 8 * (fq & 1) + 4 * n);
;                                 f32x4 p; p[0] = __shfl_xor(x[bj][n][0], 32); p[1] = __shfl_xor(x[bj][n][1], 32); p[2] = __shfl_xor(x[bj][n][2], 32); p[3] = __shfl_xor(x[bj][n][3], 32);
;                                 const f32x4 sgn = (fq < 2) ? -sn : sn;
;                                 x[bj][n] = x[bj][n] * cs + p * sgn;
;                             }
;                         }
;                     }
;                     bf16_t* rowp = O + (size_t)row * DIN + ocol;
; #pragma unroll
;                     for (int bj = 0; bj < 2; ++bj) { u32x4 wv; wv.x = cvt_pk_bf16(x[bj][0][0], x[bj][0][1]); wv.y = cvt_pk_bf16(x[bj][0][2], x[bj][0][3]); wv.z = cvt_pk_bf16(x[bj][1][0], x[bj][1][1]); wv.w = cvt_pk_bf16(x[bj][1][2], x[bj][1][3]);
;                         *(u32x4*)(rowp + 32 * bj) = wv; }
	v_add_f32_e32 v0, v0, v82
	v_fmamk_f32 v0, v0, 0x3c800000, v216
	v_mul_f32_e32 v71, 0x4f800000, v0
	v_cmp_gt_f32_e32 vcc, s69, v0
	v_cvt_pk_bf16_f32 v70, v86, v87
	s_nop 1
	v_cndmask_b32_e32 v0, v0, v71, vcc
	v_sqrt_f32_e32 v78, v0
	v_cvt_pk_bf16_f32 v71, v74, v75
	v_cvt_pk_bf16_f32 v72, v88, v89
	v_cvt_pk_bf16_f32 v73, v76, v77
	flat_store_dwordx4 v[90:91], v[70:73] offset:64
	v_add_u32_e32 v74, -1, v78
	v_fma_f32 v75, -v74, v78, v0
	v_cmp_ge_f32_e64 s[0:1], 0, v75
	v_add_u32_e32 v75, 1, v78
	v_fma_f32 v76, -v75, v78, v0
	v_cndmask_b32_e64 v74, v78, v74, s[0:1]
	v_cmp_lt_f32_e64 s[0:1], 0, v76
	v_add_u32_e32 v77, 0xffffdf80, v173
	s_nop 0
	v_cndmask_b32_e64 v74, v74, v75, s[0:1]
	v_mul_f32_e32 v75, 0x37800000, v74
	v_cndmask_b32_e32 v74, v74, v75, vcc
	v_cmp_class_f32_e32 vcc, v0, v217
	s_nop 1
	v_cndmask_b32_e32 v0, v74, v0, vcc
	v_div_scale_f32 v75, s[0:1], v0, v0, 1.0
	v_rcp_f32_e32 v76, v75
	s_movk_i32 s0, 0x207f
	v_add_u32_e32 v74, 0x80, v173
	v_fma_f32 v70, -v75, v76, 1.0
	v_fmac_f32_e32 v76, v70, v76
	v_div_scale_f32 v70, vcc, 1.0, v0, 1.0
	v_mul_f32_e32 v71, v70, v76
	v_fma_f32 v72, -v75, v71, v70
	v_fmac_f32_e32 v71, v72, v76
	v_fma_f32 v70, -v75, v71, v70
	v_div_fmas_f32 v70, v70, v76, v71
	v_div_fixup_f32 v0, v70, v0, 1.0
	v_pk_mul_f32 v[70:71], v[66:67], v[0:1] op_sel_hi:[1,0]
	v_pk_mul_f32 v[66:67], v[68:69], v[0:1] op_sel_hi:[1,0]
	v_pk_mul_f32 v[68:69], v[164:165], v[70:71]
	v_pk_mul_f32 v[70:71], v[62:63], v[0:1] op_sel_hi:[1,0]
	v_cmp_lt_i32_e32 vcc, s0, v173
	v_pk_mul_f32 v[62:63], v[64:65], v[0:1] op_sel_hi:[1,0]
	v_pk_mul_f32 v[64:65], v[160:161], v[70:71]
	v_pk_mul_f32 v[70:71], v[58:59], v[0:1] op_sel_hi:[1,0]
	v_pk_mul_f32 v[58:59], v[60:61], v[0:1] op_sel_hi:[1,0]
	v_pk_mul_f32 v[54:55], v[54:55], v[0:1] op_sel_hi:[1,0]
	v_pk_mul_f32 v[56:57], v[56:57], v[0:1] op_sel_hi:[1,0]
	v_cndmask_b32_e32 v0, v74, v77, vcc
	v_pk_mul_f32 v[66:67], v[162:163], v[66:67]
	v_pk_mul_f32 v[62:63], v[158:159], v[62:63]
	v_pk_mul_f32 v[58:59], v[138:139], v[58:59]
	v_pk_mul_f32 v[60:61], v[140:141], v[70:71]
	v_pk_mul_f32 v[70:71], v[134:135], v[56:57]
	v_pk_mul_f32 v[72:73], v[136:137], v[54:55]
	v_cmp_gt_i32_e32 vcc, s66, v0
	s_and_saveexec_b64 s[0:1], vcc
	s_cbranch_execz .LBB0_268
	v_ashrrev_i32_e32 v54, 2, v0
	v_and_b32_e32 v54, -16, v54
	v_ashrrev_i32_e32 v55, 31, v54
	v_lshlrev_b64 v[54:55], 2, v[54:55]
	v_lshl_add_u64 v[80:81], v[150:151], 0, v[54:55]
	v_lshl_add_u64 v[82:83], v[152:153], 0, v[54:55]
	flat_load_dwordx4 v[54:57], v[80:81]
	flat_load_dwordx4 v[76:79], v[82:83]
	flat_load_dwordx4 v[240:243], v[80:81] offset:16
	flat_load_dwordx4 v[244:247], v[82:83] offset:16
	ds_bpermute_b32 v84, v174, v68
	ds_bpermute_b32 v85, v174, v69
	ds_bpermute_b32 v86, v174, v66
	ds_bpermute_b32 v87, v174, v67
	v_lshlrev_b32_e32 v0, 6, v0
	v_and_b32_e32 v0, 0x3c0, v0
	s_waitcnt vmcnt(0) lgkmcnt(0)
	v_xor_b32_e32 v75, 0x80000000, v76
	v_xor_b32_e32 v88, 0x80000000, v77
	v_xor_b32_e32 v89, 0x80000000, v78
	v_xor_b32_e32 v90, 0x80000000, v79
	v_cndmask_b32_e64 v79, v79, v90, s[4:5]
	v_cndmask_b32_e64 v78, v78, v89, s[4:5]
	v_cndmask_b32_e64 v77, v77, v88, s[4:5]
	v_cndmask_b32_e64 v76, v76, v75, s[4:5]
	v_pk_mul_f32 v[76:77], v[76:77], v[84:85]
	v_pk_mul_f32 v[78:79], v[78:79], v[86:87]
	v_pk_fma_f32 v[68:69], v[68:69], v[54:55], v[76:77]
	v_pk_fma_f32 v[66:67], v[66:67], v[56:57], v[78:79]
	ds_bpermute_b32 v80, v174, v64
	ds_bpermute_b32 v81, v174, v65
	ds_bpermute_b32 v82, v174, v62
	ds_bpermute_b32 v83, v174, v63
	ds_bpermute_b32 v87, v174, v59
	s_waitcnt vmcnt(0) lgkmcnt(0)
	v_xor_b32_e32 v75, 0x80000000, v244
	v_xor_b32_e32 v84, 0x80000000, v245
	v_xor_b32_e32 v85, 0x80000000, v246
	v_xor_b32_e32 v86, 0x80000000, v247
	v_cndmask_b32_e64 v247, v247, v86, s[4:5]
	v_cndmask_b32_e64 v246, v246, v85, s[4:5]
	v_cndmask_b32_e64 v245, v245, v84, s[4:5]
	v_cndmask_b32_e64 v244, v244, v75, s[4:5]
	v_pk_mul_f32 v[244:245], v[244:245], v[80:81]
	v_pk_mul_f32 v[246:247], v[246:247], v[82:83]
	v_lshl_add_u64 v[80:81], v[150:151], 0, v[0:1]
	v_pk_fma_f32 v[62:63], v[62:63], v[242:243], v[246:247]
	v_pk_fma_f32 v[64:65], v[64:65], v[240:241], v[244:245]
	v_lshl_add_u64 v[82:83], v[152:153], 0, v[0:1]
	flat_load_dwordx4 v[54:57], v[80:81]
	flat_load_dwordx4 v[76:79], v[82:83]
	flat_load_dwordx4 v[240:243], v[80:81] offset:16
	flat_load_dwordx4 v[244:247], v[82:83] offset:16
	ds_bpermute_b32 v84, v174, v60
	ds_bpermute_b32 v85, v174, v61
	ds_bpermute_b32 v86, v174, v58
	s_waitcnt vmcnt(0) lgkmcnt(0)
	v_xor_b32_e32 v0, 0x80000000, v76
	v_xor_b32_e32 v75, 0x80000000, v77
	v_xor_b32_e32 v88, 0x80000000, v78
	v_xor_b32_e32 v89, 0x80000000, v79
	v_cndmask_b32_e64 v79, v79, v89, s[4:5]
	v_cndmask_b32_e64 v78, v78, v88, s[4:5]
	v_cndmask_b32_e64 v77, v77, v75, s[4:5]
	v_cndmask_b32_e64 v76, v76, v0, s[4:5]
	v_pk_mul_f32 v[76:77], v[76:77], v[84:85]
	v_pk_mul_f32 v[78:79], v[78:79], v[86:87]
	v_pk_fma_f32 v[60:61], v[60:61], v[54:55], v[76:77]
	v_pk_fma_f32 v[58:59], v[58:59], v[56:57], v[78:79]
	ds_bpermute_b32 v80, v174, v72
	ds_bpermute_b32 v81, v174, v73
	ds_bpermute_b32 v82, v174, v70
	ds_bpermute_b32 v83, v174, v71
	s_waitcnt vmcnt(0) lgkmcnt(0)
	v_xor_b32_e32 v0, 0x80000000, v244
	v_xor_b32_e32 v75, 0x80000000, v245
	v_xor_b32_e32 v84, 0x80000000, v246
	v_xor_b32_e32 v85, 0x80000000, v247
	v_cndmask_b32_e64 v247, v247, v85, s[4:5]
	v_cndmask_b32_e64 v246, v246, v84, s[4:5]
	v_cndmask_b32_e64 v245, v245, v75, s[4:5]
	v_cndmask_b32_e64 v244, v244, v0, s[4:5]
	v_pk_mul_f32 v[244:245], v[244:245], v[80:81]
	v_pk_mul_f32 v[246:247], v[246:247], v[82:83]
	v_pk_fma_f32 v[72:73], v[72:73], v[240:241], v[244:245]
	v_pk_fma_f32 v[70:71], v[70:71], v[242:243], v[246:247]
;     __device__ __forceinline__ void operator()(const f32x4 (&acc)[2][2][4][2], const Unit& u, int wr, int wc, int fr, int fq) const {
;     ...
;                 for (int m = 0; m < 4; ++m) {
;                     const int row = row0 + ai * HALF + m * 16;
;                     const int w = row >= RPB ? row - RPB : row;
;                     f32x4 x[2][2]; float ss = 0.f;
; #pragma unroll
;                     for (int bj = 0; bj < 2; ++bj)
; #pragma unroll
;                         for (int n = 0; n < 2; ++n) { x[bj][n] = acc[ai][bj][m][n]; const f32x4 q = x[bj][n] * x[bj][n]; ss += (q[0] + q[1]) + (q[2] + q[3]); }
;                     ss += __shfl_xor(ss, 16); ss += __shfl_xor(ss, 32);
;                     const float rinv = 1.0f / sqrtf(ss * (1.0f / 64.0f) + LN_EPS);
; #pragma unroll
;                     for (int bj = 0; bj < 2; ++bj)
; #pragma unroll
;                         for (int n = 0; n < 2; ++n) x[bj][n] = x[bj][n] * rinv * gv[bj][n];
;                     if (w < SEQ) {
; #pragma unroll
;                         for (int bj = 0; bj < 2; ++bj) {
;                             const int pos = bj ? (w & 63) : (w >> 6);
; #pragma unroll
;                             for (int n = 0; n < 2; ++n) {
;                                 const f32x4 cs = *(const f32x4*)(tcos + pos * 16 + 8 * (fq & 1) + 4 * n);
;                                 const f32x4 sn = *(const f32x4*)(tsin + pos * 16 + 8 * (fq & 1) + 4 * n);
;                                 f32x4 p; p[0] = __shfl_xor(x[bj][n][0], 32); p[1] = __shfl_xor(x[bj][n][1], 32); p[2] = __shfl_xor(x[bj][n][2], 32); p[3] = __shfl_xor(x[bj][n][3], 32);
;                                 const f32x4 sgn = (fq < 2) ? -sn : sn;
;                                 x[bj][n] = x[bj][n] * cs + p * sgn;
;                             }
;                         }
;                     }
;                     bf16_t* rowp = O + (size_t)row * DIN + ocol;
; #pragma unroll
;                     for (int bj = 0; bj < 2; ++bj) { u32x4 wv; wv.x = cvt_pk_bf16(x[bj][0][0], x[bj][0][1]); wv.y = cvt_pk_bf16(x[bj][0][2], x[bj][0][3]); wv.z = cvt_pk_bf16(x[bj][1][0], x[bj][1][1]); wv.w = cvt_pk_bf16(x[bj][1][2], x[bj][1][3]);
;                         *(u32x4*)(rowp + 32 * bj) = wv; }
.LBB0_268:
	s_or_b64 exec, exec, s[0:1]
	v_mov_b64_e32 v[54:55], s[12:13]
	v_mad_i64_i32 v[54:55], s[0:1], v74, s80, v[54:55]
	v_lshl_add_u64 v[74:75], v[118:119], 1, v[54:55]
	v_cvt_pk_bf16_f32 v54, v68, v69
	v_cvt_pk_bf16_f32 v55, v66, v67
	v_cvt_pk_bf16_f32 v56, v64, v65
	v_cvt_pk_bf16_f32 v57, v62, v63
	flat_store_dwordx4 v[74:75], v[54:57]
	v_pk_mul_f32 v[64:65], v[40:41], v[40:41]
	v_pk_mul_f32 v[66:67], v[38:39], v[38:39]
	v_cvt_pk_bf16_f32 v54, v60, v61
	v_cvt_pk_bf16_f32 v55, v58, v59
	v_cvt_pk_bf16_f32 v56, v72, v73
	v_cvt_pk_bf16_f32 v57, v70, v71
	flat_store_dwordx4 v[74:75], v[54:57] offset:64
	s_movk_i32 s0, 0x206f
	v_add_u32_e32 v58, 0x90, v173
	v_pk_mul_f32 v[54:55], v[52:53], v[52:53]
	v_pk_mul_f32 v[56:57], v[50:51], v[50:51]
	v_add_u32_e32 v59, 0xffffdf90, v173
	v_pk_mov_b32 v[60:61], v[56:57], v[54:55] op_sel:[1,0]
	v_mov_b32_e32 v57, v55
	v_pk_add_f32 v[54:55], v[60:61], v[56:57]
	v_pk_mul_f32 v[56:57], v[48:49], v[48:49]
	v_pk_mul_f32 v[60:61], v[46:47], v[46:47]
	v_pk_add_f32 v[54:55], v[54:55], v[54:55] op_sel_hi:[0,1]
	v_pk_mov_b32 v[62:63], v[60:61], v[56:57] op_sel:[1,0]
	v_mov_b32_e32 v61, v57
	v_pk_add_f32 v[56:57], v[62:63], v[60:61]
	v_pk_mul_f32 v[60:61], v[44:45], v[44:45]
	v_pk_add_f32 v[56:57], v[56:57], v[56:57] op_sel_hi:[0,1]
	v_pk_mul_f32 v[62:63], v[42:43], v[42:43]
	v_add_f32_e32 v61, v60, v61
	v_add_f32_e32 v63, v62, v63
	v_mov_b32_e32 v62, v66
	v_mov_b32_e32 v60, v67
	v_mov_b32_e32 v56, v64
	v_mov_b32_e32 v54, v65
	v_pk_add_f32 v[60:61], v[62:63], v[60:61]
	v_pk_add_f32 v[54:55], v[56:57], v[54:55]
	v_cmp_lt_i32_e64 s[0:1], s0, v173
	v_pk_add_f32 v[54:55], v[60:61], v[54:55]
	s_nop 0
	v_add_f32_e32 v0, v54, v55
	ds_bpermute_b32 v54, v175, v0
	s_waitcnt lgkmcnt(0)
	v_add_f32_e32 v0, v0, v54
	ds_bpermute_b32 v54, v174, v0
	s_waitcnt lgkmcnt(0)
	v_add_f32_e32 v0, v0, v54
	v_fmamk_f32 v0, v0, 0x3c800000, v216
	v_cmp_gt_f32_e32 vcc, s69, v0
	v_mul_f32_e32 v54, 0x4f800000, v0
	s_nop 0
	v_cndmask_b32_e32 v0, v0, v54, vcc
	v_sqrt_f32_e32 v54, v0
	s_nop 0
	v_add_u32_e32 v55, -1, v54
	v_fma_f32 v56, -v55, v54, v0
	v_cmp_ge_f32_e64 s[8:9], 0, v56
	v_add_u32_e32 v56, 1, v54
	s_nop 0
	v_cndmask_b32_e64 v55, v54, v55, s[8:9]
	v_fma_f32 v54, -v56, v54, v0
	v_cmp_lt_f32_e64 s[8:9], 0, v54
	s_nop 1
	v_cndmask_b32_e64 v54, v55, v56, s[8:9]
	v_mul_f32_e32 v55, 0x37800000, v54
	v_cndmask_b32_e32 v54, v54, v55, vcc
	v_cmp_class_f32_e32 vcc, v0, v217
	s_nop 1
	v_cndmask_b32_e32 v0, v54, v0, vcc
	v_div_scale_f32 v54, s[2:3], v0, v0, 1.0
	v_rcp_f32_e32 v55, v54
	s_nop 0
	v_fma_f32 v56, -v54, v55, 1.0
	v_fmac_f32_e32 v55, v56, v55
	v_div_scale_f32 v56, vcc, 1.0, v0, 1.0
	v_mul_f32_e32 v57, v56, v55
	v_fma_f32 v60, -v54, v57, v56
	v_fmac_f32_e32 v57, v60, v55
	v_fma_f32 v54, -v54, v57, v56
	v_div_fmas_f32 v54, v54, v55, v57
	v_div_fixup_f32 v0, v54, v0, 1.0
	v_pk_mul_f32 v[54:55], v[50:51], v[0:1] op_sel_hi:[1,0]
	v_pk_mul_f32 v[50:51], v[52:53], v[0:1] op_sel_hi:[1,0]
	v_pk_mul_f32 v[52:53], v[164:165], v[54:55]
	v_pk_mul_f32 v[54:55], v[46:47], v[0:1] op_sel_hi:[1,0]
	v_pk_mul_f32 v[46:47], v[48:49], v[0:1] op_sel_hi:[1,0]
	v_pk_mul_f32 v[48:49], v[160:161], v[54:55]
	v_pk_mul_f32 v[54:55], v[42:43], v[0:1] op_sel_hi:[1,0]
	v_pk_mul_f32 v[42:43], v[44:45], v[0:1] op_sel_hi:[1,0]
	v_pk_mul_f32 v[38:39], v[38:39], v[0:1] op_sel_hi:[1,0]
	v_pk_mul_f32 v[40:41], v[40:41], v[0:1] op_sel_hi:[1,0]
	v_cndmask_b32_e64 v0, v58, v59, s[0:1]
	v_pk_mul_f32 v[50:51], v[162:163], v[50:51]
	v_pk_mul_f32 v[46:47], v[158:159], v[46:47]
	v_pk_mul_f32 v[42:43], v[138:139], v[42:43]
	v_pk_mul_f32 v[54:55], v[140:141], v[54:55]
	v_pk_mul_f32 v[44:45], v[134:135], v[40:41]
	v_pk_mul_f32 v[56:57], v[136:137], v[38:39]
	v_cmp_gt_i32_e32 vcc, s66, v0
	s_and_saveexec_b64 s[0:1], vcc
	s_cbranch_execz .LBB0_270
	v_ashrrev_i32_e32 v38, 2, v0
	v_and_b32_e32 v38, -16, v38
	v_ashrrev_i32_e32 v39, 31, v38
	v_lshlrev_b64 v[38:39], 2, v[38:39]
	v_lshl_add_u64 v[64:65], v[150:151], 0, v[38:39]
	v_lshl_add_u64 v[66:67], v[152:153], 0, v[38:39]
	flat_load_dwordx4 v[38:41], v[64:65]
	flat_load_dwordx4 v[60:63], v[66:67]
	flat_load_dwordx4 v[240:243], v[64:65] offset:16
	flat_load_dwordx4 v[244:247], v[66:67] offset:16
	ds_bpermute_b32 v68, v174, v52
	ds_bpermute_b32 v69, v174, v53
	ds_bpermute_b32 v70, v174, v50
	ds_bpermute_b32 v71, v174, v51
	v_lshlrev_b32_e32 v0, 6, v0
	v_and_b32_e32 v0, 0x7c0, v0
	s_waitcnt vmcnt(0) lgkmcnt(0)
	v_xor_b32_e32 v59, 0x80000000, v60
	v_xor_b32_e32 v72, 0x80000000, v61
	v_xor_b32_e32 v73, 0x80000000, v62
	v_xor_b32_e32 v74, 0x80000000, v63
	v_cndmask_b32_e64 v63, v63, v74, s[4:5]
	v_cndmask_b32_e64 v62, v62, v73, s[4:5]
	v_cndmask_b32_e64 v61, v61, v72, s[4:5]
	v_cndmask_b32_e64 v60, v60, v59, s[4:5]
	v_pk_mul_f32 v[60:61], v[60:61], v[68:69]
	v_pk_mul_f32 v[62:63], v[62:63], v[70:71]
	v_pk_fma_f32 v[52:53], v[52:53], v[38:39], v[60:61]
	v_pk_fma_f32 v[50:51], v[50:51], v[40:41], v[62:63]
	ds_bpermute_b32 v64, v174, v48
	ds_bpermute_b32 v65, v174, v49
	ds_bpermute_b32 v66, v174, v46
	ds_bpermute_b32 v67, v174, v47
	ds_bpermute_b32 v71, v174, v43
	s_waitcnt vmcnt(0) lgkmcnt(0)
	v_xor_b32_e32 v59, 0x80000000, v244
	v_xor_b32_e32 v68, 0x80000000, v245
	v_xor_b32_e32 v69, 0x80000000, v246
	v_xor_b32_e32 v70, 0x80000000, v247
	v_cndmask_b32_e64 v247, v247, v70, s[4:5]
	v_cndmask_b32_e64 v246, v246, v69, s[4:5]
	v_cndmask_b32_e64 v245, v245, v68, s[4:5]
	v_cndmask_b32_e64 v244, v244, v59, s[4:5]
	v_pk_mul_f32 v[244:245], v[244:245], v[64:65]
	v_pk_mul_f32 v[246:247], v[246:247], v[66:67]
	v_lshl_add_u64 v[64:65], v[150:151], 0, v[0:1]
	v_pk_fma_f32 v[46:47], v[46:47], v[242:243], v[246:247]
	v_pk_fma_f32 v[48:49], v[48:49], v[240:241], v[244:245]
	v_lshl_add_u64 v[66:67], v[152:153], 0, v[0:1]
	flat_load_dwordx4 v[38:41], v[64:65]
	flat_load_dwordx4 v[60:63], v[66:67]
	flat_load_dwordx4 v[240:243], v[64:65] offset:16
	flat_load_dwordx4 v[244:247], v[66:67] offset:16
	ds_bpermute_b32 v68, v174, v54
	ds_bpermute_b32 v69, v174, v55
	ds_bpermute_b32 v70, v174, v42
	s_waitcnt vmcnt(0) lgkmcnt(0)
;     __device__ __forceinline__ void operator()(const f32x4 (&acc)[2][2][4][2], const Unit& u, int wr, int wc, int fr, int fq) const {
;     ...
;                 for (int m = 0; m < 4; ++m) {
;                     const int row = row0 + ai * HALF + m * 16;
;                     const int w = row >= RPB ? row - RPB : row;
;                     f32x4 x[2][2]; float ss = 0.f;
; #pragma unroll
;                     for (int bj = 0; bj < 2; ++bj)
; #pragma unroll
;                         for (int n = 0; n < 2; ++n) { x[bj][n] = acc[ai][bj][m][n]; const f32x4 q = x[bj][n] * x[bj][n]; ss += (q[0] + q[1]) + (q[2] + q[3]); }
;                     ss += __shfl_xor(ss, 16); ss += __shfl_xor(ss, 32);
;                     const float rinv = 1.0f / sqrtf(ss * (1.0f / 64.0f) + LN_EPS);
; #pragma unroll
;                     for (int bj = 0; bj < 2; ++bj)
; #pragma unroll
;                         for (int n = 0; n < 2; ++n) x[bj][n] = x[bj][n] * rinv * gv[bj][n];
;                     if (w < SEQ) {
; #pragma unroll
;                         for (int bj = 0; bj < 2; ++bj) {
;                             const int pos = bj ? (w & 63) : (w >> 6);
; #pragma unroll
;                             for (int n = 0; n < 2; ++n) {
;                                 const f32x4 cs = *(const f32x4*)(tcos + pos * 16 + 8 * (fq & 1) + 4 * n);
;                                 const f32x4 sn = *(const f32x4*)(tsin + pos * 16 + 8 * (fq & 1) + 4 * n);
;                                 f32x4 p; p[0] = __shfl_xor(x[bj][n][0], 32); p[1] = __shfl_xor(x[bj][n][1], 32); p[2] = __shfl_xor(x[bj][n][2], 32); p[3] = __shfl_xor(x[bj][n][3], 32);
;                                 const f32x4 sgn = (fq < 2) ? -sn : sn;
;                                 x[bj][n] = x[bj][n] * cs + p * sgn;
;                             }
;                         }
;                     }
;                     bf16_t* rowp = O + (size_t)row * DIN + ocol;
; #pragma unroll
;                     for (int bj = 0; bj < 2; ++bj) { u32x4 wv; wv.x = cvt_pk_bf16(x[bj][0][0], x[bj][0][1]); wv.y = cvt_pk_bf16(x[bj][0][2], x[bj][0][3]); wv.z = cvt_pk_bf16(x[bj][1][0], x[bj][1][1]); wv.w = cvt_pk_bf16(x[bj][1][2], x[bj][1][3]);
;                         *(u32x4*)(rowp + 32 * bj) = wv; }
	v_xor_b32_e32 v0, 0x80000000, v60
	v_xor_b32_e32 v59, 0x80000000, v61
	v_xor_b32_e32 v72, 0x80000000, v62
	v_xor_b32_e32 v73, 0x80000000, v63
	v_cndmask_b32_e64 v63, v63, v73, s[4:5]
	v_cndmask_b32_e64 v62, v62, v72, s[4:5]
	v_cndmask_b32_e64 v61, v61, v59, s[4:5]
	v_cndmask_b32_e64 v60, v60, v0, s[4:5]
	v_pk_mul_f32 v[60:61], v[60:61], v[68:69]
	v_pk_mul_f32 v[62:63], v[62:63], v[70:71]
	v_pk_fma_f32 v[54:55], v[54:55], v[38:39], v[60:61]
	v_pk_fma_f32 v[42:43], v[42:43], v[40:41], v[62:63]
	ds_bpermute_b32 v64, v174, v56
	ds_bpermute_b32 v65, v174, v57
	ds_bpermute_b32 v66, v174, v44
	ds_bpermute_b32 v67, v174, v45
	s_waitcnt vmcnt(0) lgkmcnt(0)
	v_xor_b32_e32 v0, 0x80000000, v244
	v_xor_b32_e32 v59, 0x80000000, v245
	v_xor_b32_e32 v68, 0x80000000, v246
	v_xor_b32_e32 v69, 0x80000000, v247
	v_cndmask_b32_e64 v247, v247, v69, s[4:5]
	v_cndmask_b32_e64 v246, v246, v68, s[4:5]
	v_cndmask_b32_e64 v245, v245, v59, s[4:5]
	v_cndmask_b32_e64 v244, v244, v0, s[4:5]
	v_pk_mul_f32 v[244:245], v[244:245], v[64:65]
	v_pk_mul_f32 v[246:247], v[246:247], v[66:67]
	v_pk_fma_f32 v[56:57], v[56:57], v[240:241], v[244:245]
	v_pk_fma_f32 v[44:45], v[44:45], v[242:243], v[246:247]
.LBB0_270:
	s_or_b64 exec, exec, s[0:1]
	v_pk_mul_f32 v[40:41], v[36:37], v[36:37]
	v_pk_mul_f32 v[60:61], v[34:35], v[34:35]
	v_pk_mul_f32 v[66:67], v[24:25], v[24:25]
	v_pk_mov_b32 v[62:63], v[60:61], v[40:41] op_sel:[1,0]
	v_mov_b32_e32 v61, v41
	v_pk_add_f32 v[40:41], v[62:63], v[60:61]
	v_pk_mul_f32 v[60:61], v[32:33], v[32:33]
	v_pk_mul_f32 v[62:63], v[30:31], v[30:31]
	v_pk_add_f32 v[40:41], v[40:41], v[40:41] op_sel_hi:[0,1]
	v_pk_mov_b32 v[64:65], v[62:63], v[60:61] op_sel:[1,0]
	v_mov_b32_e32 v63, v61
	v_pk_add_f32 v[60:61], v[64:65], v[62:63]
	v_pk_mul_f32 v[62:63], v[28:29], v[28:29]
	v_pk_add_f32 v[60:61], v[60:61], v[60:61] op_sel_hi:[0,1]
	v_pk_mul_f32 v[64:65], v[26:27], v[26:27]
	v_pk_mul_f32 v[68:69], v[22:23], v[22:23]
	v_add_f32_e32 v65, v64, v65
	v_add_f32_e32 v63, v62, v63
	v_mov_b32_e32 v64, v68
	v_mov_b32_e32 v62, v69
	v_mov_b32_e32 v60, v66
	v_mov_b32_e32 v40, v67
	v_pk_add_f32 v[62:63], v[64:65], v[62:63]
	v_pk_add_f32 v[40:41], v[60:61], v[40:41]
	v_mov_b64_e32 v[38:39], s[12:13]
	v_pk_add_f32 v[40:41], v[62:63], v[40:41]
	v_mad_i64_i32 v[38:39], s[0:1], v58, s80, v[38:39]
	v_add_f32_e32 v0, v40, v41
	ds_bpermute_b32 v40, v175, v0
	v_lshl_add_u64 v[58:59], v[118:119], 1, v[38:39]
	v_cvt_pk_bf16_f32 v38, v52, v53
	v_cvt_pk_bf16_f32 v39, v50, v51
	s_waitcnt lgkmcnt(0)
	v_add_f32_e32 v0, v0, v40
	ds_bpermute_b32 v50, v174, v0
	v_cvt_pk_bf16_f32 v40, v48, v49
	v_cvt_pk_bf16_f32 v41, v46, v47
	flat_store_dwordx4 v[58:59], v[38:41]
	s_waitcnt lgkmcnt(0)
	v_add_f32_e32 v0, v0, v50
	v_fmamk_f32 v0, v0, 0x3c800000, v216
	v_mul_f32_e32 v39, 0x4f800000, v0
	v_cmp_gt_f32_e32 vcc, s69, v0
	v_cvt_pk_bf16_f32 v38, v54, v55
	s_nop 1
	v_cndmask_b32_e32 v0, v0, v39, vcc
	v_sqrt_f32_e32 v46, v0
	v_cvt_pk_bf16_f32 v39, v42, v43
	v_cvt_pk_bf16_f32 v40, v56, v57
	v_cvt_pk_bf16_f32 v41, v44, v45
	flat_store_dwordx4 v[58:59], v[38:41] offset:64
	v_add_u32_e32 v42, -1, v46
	v_fma_f32 v43, -v42, v46, v0
	v_cmp_ge_f32_e64 s[0:1], 0, v43
	v_add_u32_e32 v43, 1, v46
	v_fma_f32 v44, -v43, v46, v0
	v_cndmask_b32_e64 v42, v46, v42, s[0:1]
	v_cmp_lt_f32_e64 s[0:1], 0, v44
	v_add_u32_e32 v45, 0xffffdfa0, v173
	s_nop 0
	v_cndmask_b32_e64 v42, v42, v43, s[0:1]
	v_mul_f32_e32 v43, 0x37800000, v42
	v_cndmask_b32_e32 v42, v42, v43, vcc
	v_cmp_class_f32_e32 vcc, v0, v217
	s_nop 1
	v_cndmask_b32_e32 v0, v42, v0, vcc
	v_div_scale_f32 v43, s[0:1], v0, v0, 1.0
	v_rcp_f32_e32 v44, v43
	s_movk_i32 s0, 0x205f
	v_add_u32_e32 v42, 0xa0, v173
	v_fma_f32 v38, -v43, v44, 1.0
	v_fmac_f32_e32 v44, v38, v44
	v_div_scale_f32 v38, vcc, 1.0, v0, 1.0
	v_mul_f32_e32 v39, v38, v44
	v_fma_f32 v40, -v43, v39, v38
	v_fmac_f32_e32 v39, v40, v44
	v_fma_f32 v38, -v43, v39, v38
	v_div_fmas_f32 v38, v38, v44, v39
	v_div_fixup_f32 v0, v38, v0, 1.0
	v_pk_mul_f32 v[38:39], v[34:35], v[0:1] op_sel_hi:[1,0]
	v_pk_mul_f32 v[34:35], v[36:37], v[0:1] op_sel_hi:[1,0]
	v_pk_mul_f32 v[36:37], v[164:165], v[38:39]
	v_pk_mul_f32 v[38:39], v[30:31], v[0:1] op_sel_hi:[1,0]
	v_cmp_lt_i32_e32 vcc, s0, v173
	v_pk_mul_f32 v[30:31], v[32:33], v[0:1] op_sel_hi:[1,0]
	v_pk_mul_f32 v[32:33], v[160:161], v[38:39]
	v_pk_mul_f32 v[38:39], v[26:27], v[0:1] op_sel_hi:[1,0]
	v_pk_mul_f32 v[26:27], v[28:29], v[0:1] op_sel_hi:[1,0]
	v_pk_mul_f32 v[22:23], v[22:23], v[0:1] op_sel_hi:[1,0]
	v_pk_mul_f32 v[24:25], v[24:25], v[0:1] op_sel_hi:[1,0]
	v_cndmask_b32_e32 v0, v42, v45, vcc
	v_pk_mul_f32 v[34:35], v[162:163], v[34:35]
	v_pk_mul_f32 v[30:31], v[158:159], v[30:31]
	v_pk_mul_f32 v[26:27], v[138:139], v[26:27]
	v_pk_mul_f32 v[28:29], v[140:141], v[38:39]
	v_pk_mul_f32 v[38:39], v[134:135], v[24:25]
	v_pk_mul_f32 v[40:41], v[136:137], v[22:23]
	v_cmp_gt_i32_e32 vcc, s66, v0
	s_and_saveexec_b64 s[0:1], vcc
	s_cbranch_execz .LBB0_272
;     __device__ __forceinline__ void operator()(const f32x4 (&acc)[2][2][4][2], const Unit& u, int wr, int wc, int fr, int fq) const {
;     ...
;                 for (int m = 0; m < 4; ++m) {
;                     const int row = row0 + ai * HALF + m * 16;
;                     const int w = row >= RPB ? row - RPB : row;
;                     f32x4 x[2][2]; float ss = 0.f;
; #pragma unroll
;                     for (int bj = 0; bj < 2; ++bj)
; #pragma unroll
;                         for (int n = 0; n < 2; ++n) { x[bj][n] = acc[ai][bj][m][n]; const f32x4 q = x[bj][n] * x[bj][n]; ss += (q[0] + q[1]) + (q[2] + q[3]); }
;                     ss += __shfl_xor(ss, 16); ss += __shfl_xor(ss, 32);
;                     const float rinv = 1.0f / sqrtf(ss * (1.0f / 64.0f) + LN_EPS);
; #pragma unroll
;                     for (int bj = 0; bj < 2; ++bj)
; #pragma unroll
;                         for (int n = 0; n < 2; ++n) x[bj][n] = x[bj][n] * rinv * gv[bj][n];
;                     if (w < SEQ) {
; #pragma unroll
;                         for (int bj = 0; bj < 2; ++bj) {
;                             const int pos = bj ? (w & 63) : (w >> 6);
; #pragma unroll
;                             for (int n = 0; n < 2; ++n) {
;                                 const f32x4 cs = *(const f32x4*)(tcos + pos * 16 + 8 * (fq & 1) + 4 * n);
;                                 const f32x4 sn = *(const f32x4*)(tsin + pos * 16 + 8 * (fq & 1) + 4 * n);
;                                 f32x4 p; p[0] = __shfl_xor(x[bj][n][0], 32); p[1] = __shfl_xor(x[bj][n][1], 32); p[2] = __shfl_xor(x[bj][n][2], 32); p[3] = __shfl_xor(x[bj][n][3], 32);
;                                 const f32x4 sgn = (fq < 2) ? -sn : sn;
;                                 x[bj][n] = x[bj][n] * cs + p * sgn;
;                             }
;                         }
;                     }
;                     bf16_t* rowp = O + (size_t)row * DIN + ocol;
; #pragma unroll
;                     for (int bj = 0; bj < 2; ++bj) { u32x4 wv; wv.x = cvt_pk_bf16(x[bj][0][0], x[bj][0][1]); wv.y = cvt_pk_bf16(x[bj][0][2], x[bj][0][3]); wv.z = cvt_pk_bf16(x[bj][1][0], x[bj][1][1]); wv.w = cvt_pk_bf16(x[bj][1][2], x[bj][1][3]);
;                         *(u32x4*)(rowp + 32 * bj) = wv; }
	v_ashrrev_i32_e32 v22, 2, v0
	v_and_b32_e32 v22, -16, v22
	v_ashrrev_i32_e32 v23, 31, v22
	v_lshlrev_b64 v[22:23], 2, v[22:23]
	v_lshl_add_u64 v[48:49], v[150:151], 0, v[22:23]
	v_lshl_add_u64 v[50:51], v[152:153], 0, v[22:23]
	flat_load_dwordx4 v[22:25], v[48:49]
	flat_load_dwordx4 v[44:47], v[50:51]
	flat_load_dwordx4 v[240:243], v[48:49] offset:16
	flat_load_dwordx4 v[244:247], v[50:51] offset:16
	ds_bpermute_b32 v52, v174, v36
	ds_bpermute_b32 v53, v174, v37
	ds_bpermute_b32 v54, v174, v34
	ds_bpermute_b32 v55, v174, v35
	v_lshlrev_b32_e32 v0, 6, v0
	v_and_b32_e32 v0, 0xbc0, v0
	s_waitcnt vmcnt(0) lgkmcnt(0)
	v_xor_b32_e32 v43, 0x80000000, v44
	v_xor_b32_e32 v56, 0x80000000, v45
	v_xor_b32_e32 v57, 0x80000000, v46
	v_xor_b32_e32 v58, 0x80000000, v47
	v_cndmask_b32_e64 v47, v47, v58, s[4:5]
	v_cndmask_b32_e64 v46, v46, v57, s[4:5]
	v_cndmask_b32_e64 v45, v45, v56, s[4:5]
	v_cndmask_b32_e64 v44, v44, v43, s[4:5]
	v_pk_mul_f32 v[44:45], v[44:45], v[52:53]
	v_pk_mul_f32 v[46:47], v[46:47], v[54:55]
	v_pk_fma_f32 v[36:37], v[36:37], v[22:23], v[44:45]
	v_pk_fma_f32 v[34:35], v[34:35], v[24:25], v[46:47]
	ds_bpermute_b32 v48, v174, v32
	ds_bpermute_b32 v49, v174, v33
	ds_bpermute_b32 v50, v174, v30
	ds_bpermute_b32 v51, v174, v31
	ds_bpermute_b32 v55, v174, v27
	s_waitcnt vmcnt(0) lgkmcnt(0)
	v_xor_b32_e32 v43, 0x80000000, v244
	v_xor_b32_e32 v52, 0x80000000, v245
	v_xor_b32_e32 v53, 0x80000000, v246
	v_xor_b32_e32 v54, 0x80000000, v247
	v_cndmask_b32_e64 v247, v247, v54, s[4:5]
	v_cndmask_b32_e64 v246, v246, v53, s[4:5]
	v_cndmask_b32_e64 v245, v245, v52, s[4:5]
	v_cndmask_b32_e64 v244, v244, v43, s[4:5]
	v_pk_mul_f32 v[244:245], v[244:245], v[48:49]
	v_pk_mul_f32 v[246:247], v[246:247], v[50:51]
	v_lshl_add_u64 v[48:49], v[150:151], 0, v[0:1]
	v_pk_fma_f32 v[30:31], v[30:31], v[242:243], v[246:247]
	v_pk_fma_f32 v[32:33], v[32:33], v[240:241], v[244:245]
	v_lshl_add_u64 v[50:51], v[152:153], 0, v[0:1]
	flat_load_dwordx4 v[22:25], v[48:49]
	flat_load_dwordx4 v[44:47], v[50:51]
	flat_load_dwordx4 v[240:243], v[48:49] offset:16
	flat_load_dwordx4 v[244:247], v[50:51] offset:16
	ds_bpermute_b32 v52, v174, v28
	ds_bpermute_b32 v53, v174, v29
	ds_bpermute_b32 v54, v174, v26
	s_waitcnt vmcnt(0) lgkmcnt(0)
	v_xor_b32_e32 v0, 0x80000000, v44
	v_xor_b32_e32 v43, 0x80000000, v45
	v_xor_b32_e32 v56, 0x80000000, v46
	v_xor_b32_e32 v57, 0x80000000, v47
	v_cndmask_b32_e64 v47, v47, v57, s[4:5]
	v_cndmask_b32_e64 v46, v46, v56, s[4:5]
	v_cndmask_b32_e64 v45, v45, v43, s[4:5]
	v_cndmask_b32_e64 v44, v44, v0, s[4:5]
	v_pk_mul_f32 v[44:45], v[44:45], v[52:53]
	v_pk_mul_f32 v[46:47], v[46:47], v[54:55]
	v_pk_fma_f32 v[28:29], v[28:29], v[22:23], v[44:45]
	v_pk_fma_f32 v[26:27], v[26:27], v[24:25], v[46:47]
	ds_bpermute_b32 v48, v174, v40
	ds_bpermute_b32 v49, v174, v41
	ds_bpermute_b32 v50, v174, v38
	ds_bpermute_b32 v51, v174, v39
	s_waitcnt vmcnt(0) lgkmcnt(0)
	v_xor_b32_e32 v0, 0x80000000, v244
	v_xor_b32_e32 v43, 0x80000000, v245
	v_xor_b32_e32 v52, 0x80000000, v246
	v_xor_b32_e32 v53, 0x80000000, v247
	v_cndmask_b32_e64 v247, v247, v53, s[4:5]
	v_cndmask_b32_e64 v246, v246, v52, s[4:5]
	v_cndmask_b32_e64 v245, v245, v43, s[4:5]
	v_cndmask_b32_e64 v244, v244, v0, s[4:5]
	v_pk_mul_f32 v[244:245], v[244:245], v[48:49]
	v_pk_mul_f32 v[246:247], v[246:247], v[50:51]
	v_pk_fma_f32 v[40:41], v[40:41], v[240:241], v[244:245]
	v_pk_fma_f32 v[38:39], v[38:39], v[242:243], v[246:247]
.LBB0_272:
	s_or_b64 exec, exec, s[0:1]
	v_mov_b64_e32 v[22:23], s[12:13]
	v_mad_i64_i32 v[22:23], s[0:1], v42, s80, v[22:23]
	v_lshl_add_u64 v[42:43], v[118:119], 1, v[22:23]
	v_cvt_pk_bf16_f32 v22, v36, v37
	v_cvt_pk_bf16_f32 v23, v34, v35
	v_cvt_pk_bf16_f32 v24, v32, v33
	v_cvt_pk_bf16_f32 v25, v30, v31
	flat_store_dwordx4 v[42:43], v[22:25]
	v_pk_mul_f32 v[32:33], v[4:5], v[4:5]
	v_pk_mul_f32 v[34:35], v[2:3], v[2:3]
	v_cvt_pk_bf16_f32 v22, v28, v29
	v_cvt_pk_bf16_f32 v23, v26, v27
	v_cvt_pk_bf16_f32 v24, v40, v41
	v_cvt_pk_bf16_f32 v25, v38, v39
	flat_store_dwordx4 v[42:43], v[22:25] offset:64
	s_movk_i32 s0, 0x204f
	v_add_u32_e32 v26, 0xb0, v173
	v_pk_mul_f32 v[22:23], v[20:21], v[20:21]
	v_pk_mul_f32 v[24:25], v[18:19], v[18:19]
	v_add_u32_e32 v27, 0xffffdfb0, v173
	v_pk_mov_b32 v[28:29], v[24:25], v[22:23] op_sel:[1,0]
	v_mov_b32_e32 v25, v23
	v_pk_add_f32 v[22:23], v[28:29], v[24:25]
	v_pk_mul_f32 v[24:25], v[12:13], v[12:13]
	v_pk_mul_f32 v[28:29], v[10:11], v[10:11]
	v_pk_add_f32 v[22:23], v[22:23], v[22:23] op_sel_hi:[0,1]
	v_pk_mov_b32 v[30:31], v[28:29], v[24:25] op_sel:[1,0]
	v_mov_b32_e32 v29, v25
	v_pk_add_f32 v[24:25], v[30:31], v[28:29]
	v_pk_mul_f32 v[28:29], v[8:9], v[8:9]
	v_pk_add_f32 v[24:25], v[24:25], v[24:25] op_sel_hi:[0,1]
	v_pk_mul_f32 v[30:31], v[6:7], v[6:7]
	v_add_f32_e32 v29, v28, v29
	v_add_f32_e32 v31, v30, v31
	v_mov_b32_e32 v30, v34
	v_mov_b32_e32 v28, v35
	v_mov_b32_e32 v24, v32
	v_mov_b32_e32 v22, v33
	v_pk_add_f32 v[28:29], v[30:31], v[28:29]
	v_pk_add_f32 v[22:23], v[24:25], v[22:23]
	v_cmp_lt_i32_e64 s[0:1], s0, v173
	v_pk_add_f32 v[22:23], v[28:29], v[22:23]
	s_nop 0
	v_add_f32_e32 v0, v22, v23
	ds_bpermute_b32 v22, v175, v0
	s_waitcnt lgkmcnt(0)
	v_add_f32_e32 v0, v0, v22
	ds_bpermute_b32 v22, v174, v0
	s_waitcnt lgkmcnt(0)
;     __device__ __forceinline__ void operator()(const f32x4 (&acc)[2][2][4][2], const Unit& u, int wr, int wc, int fr, int fq) const {
;     ...
;                 for (int m = 0; m < 4; ++m) {
;                     const int row = row0 + ai * HALF + m * 16;
;                     const int w = row >= RPB ? row - RPB : row;
;                     f32x4 x[2][2]; float ss = 0.f;
; #pragma unroll
;                     for (int bj = 0; bj < 2; ++bj)
; #pragma unroll
;                         for (int n = 0; n < 2; ++n) { x[bj][n] = acc[ai][bj][m][n]; const f32x4 q = x[bj][n] * x[bj][n]; ss += (q[0] + q[1]) + (q[2] + q[3]); }
;                     ss += __shfl_xor(ss, 16); ss += __shfl_xor(ss, 32);
;                     const float rinv = 1.0f / sqrtf(ss * (1.0f / 64.0f) + LN_EPS);
; #pragma unroll
;                     for (int bj = 0; bj < 2; ++bj)
; #pragma unroll
;                         for (int n = 0; n < 2; ++n) x[bj][n] = x[bj][n] * rinv * gv[bj][n];
;                     if (w < SEQ) {
; #pragma unroll
;                         for (int bj = 0; bj < 2; ++bj) {
;                             const int pos = bj ? (w & 63) : (w >> 6);
; #pragma unroll
;                             for (int n = 0; n < 2; ++n) {
;                                 const f32x4 cs = *(const f32x4*)(tcos + pos * 16 + 8 * (fq & 1) + 4 * n);
;                                 const f32x4 sn = *(const f32x4*)(tsin + pos * 16 + 8 * (fq & 1) + 4 * n);
;                                 f32x4 p; p[0] = __shfl_xor(x[bj][n][0], 32); p[1] = __shfl_xor(x[bj][n][1], 32); p[2] = __shfl_xor(x[bj][n][2], 32); p[3] = __shfl_xor(x[bj][n][3], 32);
;                                 const f32x4 sgn = (fq < 2) ? -sn : sn;
;                                 x[bj][n] = x[bj][n] * cs + p * sgn;
;                             }
;                         }
;                     }
;                     bf16_t* rowp = O + (size_t)row * DIN + ocol;
; #pragma unroll
;                     for (int bj = 0; bj < 2; ++bj) { u32x4 wv; wv.x = cvt_pk_bf16(x[bj][0][0], x[bj][0][1]); wv.y = cvt_pk_bf16(x[bj][0][2], x[bj][0][3]); wv.z = cvt_pk_bf16(x[bj][1][0], x[bj][1][1]); wv.w = cvt_pk_bf16(x[bj][1][2], x[bj][1][3]);
;                         *(u32x4*)(rowp + 32 * bj) = wv; }
	v_add_f32_e32 v0, v0, v22
	v_fmamk_f32 v0, v0, 0x3c800000, v216
	v_cmp_gt_f32_e32 vcc, s69, v0
	v_mul_f32_e32 v22, 0x4f800000, v0
	s_nop 0
	v_cndmask_b32_e32 v0, v0, v22, vcc
	v_sqrt_f32_e32 v22, v0
	s_nop 0
	v_add_u32_e32 v23, -1, v22
	v_fma_f32 v24, -v23, v22, v0
	v_cmp_ge_f32_e64 s[8:9], 0, v24
	v_add_u32_e32 v24, 1, v22
	s_nop 0
	v_cndmask_b32_e64 v23, v22, v23, s[8:9]
	v_fma_f32 v22, -v24, v22, v0
	v_cmp_lt_f32_e64 s[8:9], 0, v22
	s_nop 1
	v_cndmask_b32_e64 v22, v23, v24, s[8:9]
	v_mul_f32_e32 v23, 0x37800000, v22
	v_cndmask_b32_e32 v22, v22, v23, vcc
	v_cmp_class_f32_e32 vcc, v0, v217
	s_nop 1
	v_cndmask_b32_e32 v0, v22, v0, vcc
	v_div_scale_f32 v22, s[2:3], v0, v0, 1.0
	v_rcp_f32_e32 v23, v22
	s_nop 0
	v_fma_f32 v24, -v22, v23, 1.0
	v_fmac_f32_e32 v23, v24, v23
	v_div_scale_f32 v24, vcc, 1.0, v0, 1.0
	v_mul_f32_e32 v25, v24, v23
	v_fma_f32 v28, -v22, v25, v24
	v_fmac_f32_e32 v25, v28, v23
	v_fma_f32 v22, -v22, v25, v24
	v_div_fmas_f32 v22, v22, v23, v25
	v_div_fixup_f32 v0, v22, v0, 1.0
	v_pk_mul_f32 v[22:23], v[18:19], v[0:1] op_sel_hi:[1,0]
	v_pk_mul_f32 v[18:19], v[20:21], v[0:1] op_sel_hi:[1,0]
	v_pk_mul_f32 v[20:21], v[164:165], v[22:23]
	v_pk_mul_f32 v[22:23], v[10:11], v[0:1] op_sel_hi:[1,0]
	v_pk_mul_f32 v[10:11], v[12:13], v[0:1] op_sel_hi:[1,0]
	v_pk_mul_f32 v[12:13], v[6:7], v[0:1] op_sel_hi:[1,0]
	v_pk_mul_f32 v[6:7], v[8:9], v[0:1] op_sel_hi:[1,0]
	v_pk_mul_f32 v[2:3], v[2:3], v[0:1] op_sel_hi:[1,0]
	v_pk_mul_f32 v[4:5], v[4:5], v[0:1] op_sel_hi:[1,0]
	v_cndmask_b32_e64 v0, v26, v27, s[0:1]
	v_pk_mul_f32 v[18:19], v[162:163], v[18:19]
	v_pk_mul_f32 v[10:11], v[158:159], v[10:11]
	v_pk_mul_f32 v[22:23], v[160:161], v[22:23]
	v_pk_mul_f32 v[6:7], v[138:139], v[6:7]
	v_pk_mul_f32 v[12:13], v[140:141], v[12:13]
	v_pk_mul_f32 v[8:9], v[134:135], v[4:5]
	v_pk_mul_f32 v[24:25], v[136:137], v[2:3]
	v_cmp_gt_i32_e32 vcc, s66, v0
	s_and_saveexec_b64 s[0:1], vcc
	s_cbranch_execz .LBB0_274
	v_ashrrev_i32_e32 v2, 2, v0
	v_and_b32_e32 v2, -16, v2
	v_ashrrev_i32_e32 v3, 31, v2
	v_lshlrev_b64 v[2:3], 2, v[2:3]
	v_lshl_add_u64 v[32:33], v[150:151], 0, v[2:3]
	v_lshl_add_u64 v[34:35], v[152:153], 0, v[2:3]
	flat_load_dwordx4 v[2:5], v[32:33]
	flat_load_dwordx4 v[28:31], v[34:35]
	flat_load_dwordx4 v[240:243], v[32:33] offset:16
	flat_load_dwordx4 v[244:247], v[34:35] offset:16
	ds_bpermute_b32 v36, v174, v20
	ds_bpermute_b32 v37, v174, v21
	ds_bpermute_b32 v38, v174, v18
	ds_bpermute_b32 v39, v174, v19
	v_lshlrev_b32_e32 v0, 6, v0
	v_and_b32_e32 v0, 0xfc0, v0
	s_waitcnt vmcnt(0) lgkmcnt(0)
	v_xor_b32_e32 v27, 0x80000000, v28
	v_xor_b32_e32 v40, 0x80000000, v29
	v_xor_b32_e32 v41, 0x80000000, v30
	v_xor_b32_e32 v42, 0x80000000, v31
	v_cndmask_b32_e64 v31, v31, v42, s[4:5]
	v_cndmask_b32_e64 v30, v30, v41, s[4:5]
	v_cndmask_b32_e64 v29, v29, v40, s[4:5]
	v_cndmask_b32_e64 v28, v28, v27, s[4:5]
	v_pk_mul_f32 v[28:29], v[28:29], v[36:37]
	v_pk_mul_f32 v[30:31], v[30:31], v[38:39]
	v_pk_fma_f32 v[20:21], v[20:21], v[2:3], v[28:29]
	v_pk_fma_f32 v[18:19], v[18:19], v[4:5], v[30:31]
	ds_bpermute_b32 v32, v174, v22
	ds_bpermute_b32 v33, v174, v23
	ds_bpermute_b32 v34, v174, v10
	ds_bpermute_b32 v35, v174, v11
	ds_bpermute_b32 v39, v174, v7
	s_waitcnt vmcnt(0) lgkmcnt(0)
	v_xor_b32_e32 v27, 0x80000000, v244
	v_xor_b32_e32 v36, 0x80000000, v245
	v_xor_b32_e32 v37, 0x80000000, v246
	v_xor_b32_e32 v38, 0x80000000, v247
	v_cndmask_b32_e64 v247, v247, v38, s[4:5]
	v_cndmask_b32_e64 v246, v246, v37, s[4:5]
	v_cndmask_b32_e64 v245, v245, v36, s[4:5]
	v_cndmask_b32_e64 v244, v244, v27, s[4:5]
	v_pk_mul_f32 v[244:245], v[244:245], v[32:33]
	v_pk_mul_f32 v[246:247], v[246:247], v[34:35]
	v_lshl_add_u64 v[32:33], v[150:151], 0, v[0:1]
	v_pk_fma_f32 v[10:11], v[10:11], v[242:243], v[246:247]
	v_pk_fma_f32 v[22:23], v[22:23], v[240:241], v[244:245]
	v_lshl_add_u64 v[34:35], v[152:153], 0, v[0:1]
	flat_load_dwordx4 v[2:5], v[32:33]
	flat_load_dwordx4 v[28:31], v[34:35]
	flat_load_dwordx4 v[240:243], v[32:33] offset:16
	flat_load_dwordx4 v[244:247], v[34:35] offset:16
	ds_bpermute_b32 v36, v174, v12
	ds_bpermute_b32 v37, v174, v13
	ds_bpermute_b32 v38, v174, v6
	s_waitcnt vmcnt(0) lgkmcnt(0)
	v_xor_b32_e32 v0, 0x80000000, v28
	v_xor_b32_e32 v27, 0x80000000, v29
	v_xor_b32_e32 v40, 0x80000000, v30
	v_xor_b32_e32 v41, 0x80000000, v31
	v_cndmask_b32_e64 v31, v31, v41, s[4:5]
	v_cndmask_b32_e64 v30, v30, v40, s[4:5]
	v_cndmask_b32_e64 v29, v29, v27, s[4:5]
	v_cndmask_b32_e64 v28, v28, v0, s[4:5]
	v_pk_mul_f32 v[28:29], v[28:29], v[36:37]
	v_pk_mul_f32 v[30:31], v[30:31], v[38:39]
	v_pk_fma_f32 v[12:13], v[12:13], v[2:3], v[28:29]
	v_pk_fma_f32 v[6:7], v[6:7], v[4:5], v[30:31]
	ds_bpermute_b32 v32, v174, v24
	ds_bpermute_b32 v33, v174, v25
	ds_bpermute_b32 v34, v174, v8
	ds_bpermute_b32 v35, v174, v9
	s_waitcnt vmcnt(0) lgkmcnt(0)
	v_xor_b32_e32 v0, 0x80000000, v244
	v_xor_b32_e32 v27, 0x80000000, v245
	v_xor_b32_e32 v36, 0x80000000, v246
	v_xor_b32_e32 v37, 0x80000000, v247
	v_cndmask_b32_e64 v247, v247, v37, s[4:5]
	v_cndmask_b32_e64 v246, v246, v36, s[4:5]
	v_cndmask_b32_e64 v245, v245, v27, s[4:5]
	v_cndmask_b32_e64 v244, v244, v0, s[4:5]
	v_pk_mul_f32 v[244:245], v[244:245], v[32:33]
	v_pk_mul_f32 v[246:247], v[246:247], v[34:35]
	v_pk_fma_f32 v[24:25], v[24:25], v[240:241], v[244:245]
	v_pk_fma_f32 v[8:9], v[8:9], v[242:243], v[246:247]
